# norm_alow low-rank projection dot products packed: v_pk_mul/v_pk_fma_f32 with two partial sums per output (f32, reassociated)
# speedup vs baseline: 1.0035x; 1.0035x over previous
; #define LAS __attribute__((address_space(3)))
; __device__ __forceinline__ unsigned cvt_pk_bf16(float lo, float hi) { unsigned r; asm volatile("v_cvt_pk_bf16_f32 %0, %1, %2" : "=v"(r) : "v"(lo), "v"(hi)); return r; }
; __device__ void phase_norm_alow(const Params& P, int l, int half, LAS unsigned char* lds) {
;     ...
;         f32x4 v[4]; float ss = 0.f;
; #pragma unroll
;         for (int i = 0; i < 4; ++i) { v[i] = nv[i]; ss += v[i][0] * v[i][0] + v[i][1] * v[i][1] + v[i][2] * v[i][2] + v[i][3] * v[i][3]; }
;         if (row + rstride < TH) {
; #pragma unroll
;             for (int i = 0; i < 4; ++i) nv[i] = *(const f32x4*)(xs + (size_t)(row + rstride) * DM + i * 256 + lane * 4);
;         }
;         ss = wave_sum(ss);
;         const float r = rsqrtf(ss * (1.0f / DM) + EPS);
;         float a[16];
; #pragma unroll
;         for (int c = 0; c < 16; ++c) a[c] = 0.f;
; #pragma unroll
;         for (int i = 0; i < 4; ++i) { f32x4 h = v[i] * r * gv[i];
;             u32x2 w; w.x = cvt_pk_bf16(h[0], h[1]); w.y = cvt_pk_bf16(h[2], h[3]);
;             *(u32x2*)(H + (size_t)row * DM + i * 256 + lane * 4) = w;
; #pragma unroll
;             for (int c = 0; c < 16; ++c) { const f32x4 wv = *(const LAS f32x4*)(WaT + c * 1024 + i * 256 + lane * 4); a[c] += h[0] * wv[0] + h[1] * wv[1] + h[2] * wv[2] + h[3] * wv[3]; } }
.LBB0_120:
	s_or_b64 exec, exec, s[30:31]
	v_mul_f32_e32 v51, v47, v47
	v_mul_f32_e32 v58, v43, v43
	v_fmac_f32_e32 v51, v46, v46
	v_fmac_f32_e32 v58, v42, v42
	v_fmac_f32_e32 v51, v48, v48
	v_fmac_f32_e32 v58, v44, v44
	v_fmac_f32_e32 v51, v49, v49
	v_fmac_f32_e32 v58, v45, v45
	v_add_f32_e32 v51, v51, v58
	v_mul_f32_e32 v58, v39, v39
	v_fmac_f32_e32 v58, v38, v38
	v_fmac_f32_e32 v58, v40, v40
	v_fmac_f32_e32 v58, v41, v41
	v_add_f32_e32 v51, v51, v58
	v_mul_f32_e32 v58, v35, v35
	v_fmac_f32_e32 v58, v34, v34
	v_fmac_f32_e32 v58, v36, v36
	v_fmac_f32_e32 v58, v37, v37
	v_add_f32_e32 v51, v51, v58
	v_mov_b32_e32 v58, v51
	s_nop 1
	v_permlane32_swap_b32_e32 v58, v51
	s_nop 1
	v_lshl_add_u64 v[68:69], s[74:75], 0, v[56:57]
	s_waitcnt lgkmcnt(0)
	v_add_f32_e32 v51, v51, v58
	v_mov_b32_e32 v58, v51
	s_nop 1
	v_permlane16_swap_b32_e32 v58, v51
	s_nop 1
	s_waitcnt lgkmcnt(0)
	v_add_f32_e32 v51, v51, v58
	s_nop 1
	v_mov_b32_dpp v58, v51 row_ror:8 row_mask:0xf bank_mask:0xf
	s_waitcnt lgkmcnt(0)
	v_add_f32_e32 v51, v51, v58
	s_nop 1
	v_mov_b32_dpp v58, v51 row_shl:4 row_mask:0xf bank_mask:0x5
	s_nop 1
	v_mov_b32_dpp v58, v51 row_shr:4 row_mask:0xf bank_mask:0xa
	s_waitcnt lgkmcnt(0)
	v_add_f32_e32 v51, v51, v58
	s_nop 1
	v_mov_b32_dpp v58, v51 quad_perm:[2,3,0,1] row_mask:0xf bank_mask:0xf
	s_waitcnt lgkmcnt(0)
	v_add_f32_e32 v51, v51, v58
	s_nop 1
	v_mov_b32_dpp v58, v51 quad_perm:[1,0,3,2] row_mask:0xf bank_mask:0xf
	s_waitcnt lgkmcnt(0)
	v_add_f32_e32 v51, v51, v58
	v_fmamk_f32 v51, v51, 0x3a800000, v1
	v_cmp_gt_f32_e64 s[0:1], s33, v51
	v_mul_f32_e32 v58, 0x4b800000, v51
	s_nop 0
	v_cndmask_b32_e64 v51, v51, v58, s[0:1]
	v_rsq_f32_e32 v51, v51
	s_nop 0
	v_mul_f32_e32 v58, 0x45800000, v51
	v_cndmask_b32_e64 v58, v51, v58, s[0:1]
	v_pk_mul_f32 v[46:47], v[46:47], v[58:59] op_sel_hi:[1,0]
	s_mov_b32 s0, 0x5a88000
	v_pk_mul_f32 v[48:49], v[48:49], v[58:59] op_sel_hi:[1,0]
	v_pk_mul_f32 v[60:61], v[14:15], v[46:47]
	v_add_co_u32_e64 v46, s[0:1], s0, v68
	v_pk_mul_f32 v[48:49], v[16:17], v[48:49]
	v_cvt_pk_bf16_f32 v70, v60, v61
	s_nop 0
	v_addc_co_u32_e64 v47, s[0:1], 0, v69, s[0:1]
	v_cvt_pk_bf16_f32 v71, v48, v49
	global_store_dwordx2 v[46:47], v[70:71], off
	ds_read_b128 v[100:103], v67
	ds_read_b128 v[104:107], v67 offset:4096
	ds_read_b128 v[108:111], v67 offset:8192
	ds_read_b128 v[112:115], v67 offset:12288
	ds_read_b128 v[116:119], v67 offset:16384
	ds_read_b128 v[120:123], v67 offset:20480
	ds_read_b128 v[124:127], v67 offset:24576
	s_waitcnt lgkmcnt(6)
	v_pk_mul_f32 v[148:149], v[100:101], v[60:61]
	v_pk_fma_f32 v[148:149], v[102:103], v[48:49], v[148:149]
	ds_read_b128 v[128:131], v67 offset:28672
	s_waitcnt lgkmcnt(6)
	v_pk_mul_f32 v[150:151], v[104:105], v[60:61]
	v_pk_fma_f32 v[150:151], v[106:107], v[48:49], v[150:151]
	ds_read_b128 v[100:103], v67 offset:32768
	s_waitcnt lgkmcnt(6)
	v_pk_mul_f32 v[152:153], v[108:109], v[60:61]
	v_pk_fma_f32 v[152:153], v[110:111], v[48:49], v[152:153]
	ds_read_b128 v[104:107], v67 offset:36864
	s_waitcnt lgkmcnt(6)
	v_pk_mul_f32 v[154:155], v[112:113], v[60:61]
	v_pk_fma_f32 v[154:155], v[114:115], v[48:49], v[154:155]
	ds_read_b128 v[108:111], v67 offset:40960
	s_waitcnt lgkmcnt(6)
	v_pk_mul_f32 v[156:157], v[116:117], v[60:61]
	v_pk_fma_f32 v[156:157], v[118:119], v[48:49], v[156:157]
	ds_read_b128 v[112:115], v67 offset:45056
	s_waitcnt lgkmcnt(6)
	v_pk_mul_f32 v[158:159], v[120:121], v[60:61]
	v_pk_fma_f32 v[158:159], v[122:123], v[48:49], v[158:159]
	ds_read_b128 v[116:119], v67 offset:49152
	s_waitcnt lgkmcnt(6)
	v_pk_mul_f32 v[160:161], v[124:125], v[60:61]
	v_pk_fma_f32 v[160:161], v[126:127], v[48:49], v[160:161]
	ds_read_b128 v[120:123], v67 offset:53248
	s_waitcnt lgkmcnt(6)
	v_pk_mul_f32 v[162:163], v[128:129], v[60:61]
	v_pk_fma_f32 v[162:163], v[130:131], v[48:49], v[162:163]
	ds_read_b128 v[124:127], v67 offset:57344
	s_waitcnt lgkmcnt(6)
	v_pk_mul_f32 v[164:165], v[100:101], v[60:61]
	v_pk_fma_f32 v[164:165], v[102:103], v[48:49], v[164:165]
	ds_read_b128 v[128:131], v67 offset:61440
	s_waitcnt lgkmcnt(6)
	v_pk_mul_f32 v[168:169], v[104:105], v[60:61]
	v_pk_fma_f32 v[168:169], v[106:107], v[48:49], v[168:169]
	ds_read_b128 v[100:103], v67 offset:1024
	s_waitcnt lgkmcnt(6)
	v_pk_mul_f32 v[170:171], v[108:109], v[60:61]
	v_pk_fma_f32 v[170:171], v[110:111], v[48:49], v[170:171]
	ds_read_b128 v[104:107], v67 offset:5120
	s_waitcnt lgkmcnt(6)
	v_pk_mul_f32 v[172:173], v[112:113], v[60:61]
	v_pk_fma_f32 v[172:173], v[114:115], v[48:49], v[172:173]
	ds_read_b128 v[108:111], v67 offset:9216
	s_waitcnt lgkmcnt(6)
	v_pk_mul_f32 v[174:175], v[116:117], v[60:61]
	v_pk_fma_f32 v[174:175], v[118:119], v[48:49], v[174:175]
	ds_read_b128 v[112:115], v67 offset:13312
	s_waitcnt lgkmcnt(6)
	v_pk_mul_f32 v[176:177], v[120:121], v[60:61]
	v_pk_fma_f32 v[176:177], v[122:123], v[48:49], v[176:177]
	ds_read_b128 v[116:119], v67 offset:17408
	s_waitcnt lgkmcnt(6)
	v_pk_mul_f32 v[178:179], v[124:125], v[60:61]
	v_pk_fma_f32 v[178:179], v[126:127], v[48:49], v[178:179]
	ds_read_b128 v[120:123], v67 offset:21504
	s_waitcnt lgkmcnt(6)
	v_pk_mul_f32 v[180:181], v[128:129], v[60:61]
	v_pk_fma_f32 v[180:181], v[130:131], v[48:49], v[180:181]
	v_pk_mul_f32 v[60:61], v[42:43], v[58:59] op_sel_hi:[1,0]
	v_pk_mul_f32 v[42:43], v[44:45], v[58:59] op_sel_hi:[1,0]
	v_pk_mul_f32 v[44:45], v[10:11], v[60:61]
	v_pk_mul_f32 v[42:43], v[12:13], v[42:43]
	v_cvt_pk_bf16_f32 v60, v44, v45
	s_nop 0
	v_cvt_pk_bf16_f32 v61, v42, v43
	ds_read_b128 v[124:127], v67 offset:25600
	global_store_dwordx2 v[46:47], v[60:61], off offset:512
	s_waitcnt lgkmcnt(6)
; #define LAS __attribute__((address_space(3)))
; __device__ __forceinline__ unsigned cvt_pk_bf16(float lo, float hi) { unsigned r; asm volatile("v_cvt_pk_bf16_f32 %0, %1, %2" : "=v"(r) : "v"(lo), "v"(hi)); return r; }
; __device__ void phase_norm_alow(const Params& P, int l, int half, LAS unsigned char* lds) {
;     ...
;         for (int i = 0; i < 4; ++i) { f32x4 h = v[i] * r * gv[i];
;             u32x2 w; w.x = cvt_pk_bf16(h[0], h[1]); w.y = cvt_pk_bf16(h[2], h[3]);
;             *(u32x2*)(H + (size_t)row * DM + i * 256 + lane * 4) = w;
; #pragma unroll
;             for (int c = 0; c < 16; ++c) { const f32x4 wv = *(const LAS f32x4*)(WaT + c * 1024 + i * 256 + lane * 4); a[c] += h[0] * wv[0] + h[1] * wv[1] + h[2] * wv[2] + h[3] * wv[3]; } }
	v_pk_fma_f32 v[148:149], v[100:101], v[44:45], v[148:149]
	v_pk_fma_f32 v[148:149], v[102:103], v[42:43], v[148:149]
	ds_read_b128 v[128:131], v67 offset:29696
	s_waitcnt lgkmcnt(6)
	v_pk_fma_f32 v[150:151], v[104:105], v[44:45], v[150:151]
	v_pk_fma_f32 v[150:151], v[106:107], v[42:43], v[150:151]
	ds_read_b128 v[100:103], v67 offset:33792
	s_waitcnt lgkmcnt(6)
	v_pk_fma_f32 v[152:153], v[108:109], v[44:45], v[152:153]
	v_pk_fma_f32 v[152:153], v[110:111], v[42:43], v[152:153]
	ds_read_b128 v[104:107], v67 offset:37888
	s_waitcnt lgkmcnt(6)
	v_pk_fma_f32 v[154:155], v[112:113], v[44:45], v[154:155]
	v_pk_fma_f32 v[154:155], v[114:115], v[42:43], v[154:155]
	ds_read_b128 v[108:111], v67 offset:41984
	s_waitcnt lgkmcnt(6)
	v_pk_fma_f32 v[156:157], v[116:117], v[44:45], v[156:157]
	v_pk_fma_f32 v[156:157], v[118:119], v[42:43], v[156:157]
	ds_read_b128 v[112:115], v67 offset:46080
	s_waitcnt lgkmcnt(6)
	v_pk_fma_f32 v[158:159], v[120:121], v[44:45], v[158:159]
	v_pk_fma_f32 v[158:159], v[122:123], v[42:43], v[158:159]
	ds_read_b128 v[116:119], v67 offset:50176
	s_waitcnt lgkmcnt(6)
	v_pk_fma_f32 v[160:161], v[124:125], v[44:45], v[160:161]
	v_pk_fma_f32 v[160:161], v[126:127], v[42:43], v[160:161]
	ds_read_b128 v[120:123], v67 offset:54272
	s_waitcnt lgkmcnt(6)
	v_pk_fma_f32 v[162:163], v[128:129], v[44:45], v[162:163]
	v_pk_fma_f32 v[162:163], v[130:131], v[42:43], v[162:163]
	ds_read_b128 v[124:127], v67 offset:58368
	s_waitcnt lgkmcnt(6)
	v_pk_fma_f32 v[164:165], v[100:101], v[44:45], v[164:165]
	v_pk_fma_f32 v[164:165], v[102:103], v[42:43], v[164:165]
	ds_read_b128 v[128:131], v67 offset:62464
	s_waitcnt lgkmcnt(6)
	v_pk_fma_f32 v[168:169], v[104:105], v[44:45], v[168:169]
	v_pk_fma_f32 v[168:169], v[106:107], v[42:43], v[168:169]
	ds_read_b128 v[100:103], v67 offset:2048
	s_waitcnt lgkmcnt(6)
	v_pk_fma_f32 v[170:171], v[108:109], v[44:45], v[170:171]
	v_pk_fma_f32 v[170:171], v[110:111], v[42:43], v[170:171]
	ds_read_b128 v[104:107], v67 offset:6144
	s_waitcnt lgkmcnt(6)
	v_pk_fma_f32 v[172:173], v[112:113], v[44:45], v[172:173]
	v_pk_fma_f32 v[172:173], v[114:115], v[42:43], v[172:173]
	ds_read_b128 v[108:111], v67 offset:10240
	s_waitcnt lgkmcnt(6)
	v_pk_fma_f32 v[174:175], v[116:117], v[44:45], v[174:175]
	v_pk_fma_f32 v[174:175], v[118:119], v[42:43], v[174:175]
	ds_read_b128 v[112:115], v67 offset:14336
	s_waitcnt lgkmcnt(6)
	v_pk_fma_f32 v[176:177], v[120:121], v[44:45], v[176:177]
	v_pk_fma_f32 v[176:177], v[122:123], v[42:43], v[176:177]
	ds_read_b128 v[116:119], v67 offset:18432
	s_waitcnt lgkmcnt(6)
	v_pk_fma_f32 v[178:179], v[124:125], v[44:45], v[178:179]
	v_pk_fma_f32 v[178:179], v[126:127], v[42:43], v[178:179]
	ds_read_b128 v[120:123], v67 offset:22528
	s_waitcnt lgkmcnt(6)
	v_pk_fma_f32 v[180:181], v[128:129], v[44:45], v[180:181]
	v_pk_fma_f32 v[180:181], v[130:131], v[42:43], v[180:181]
	v_pk_mul_f32 v[42:43], v[38:39], v[58:59] op_sel_hi:[1,0]
	v_pk_mul_f32 v[38:39], v[40:41], v[58:59] op_sel_hi:[1,0]
	v_pk_mul_f32 v[40:41], v[6:7], v[42:43]
	v_pk_mul_f32 v[38:39], v[8:9], v[38:39]
	v_cvt_pk_bf16_f32 v42, v40, v41
	v_cvt_pk_bf16_f32 v43, v38, v39
	global_store_dwordx2 v[46:47], v[42:43], off offset:1024
	ds_read_b128 v[124:127], v67 offset:26624
	ds_read_b128 v[128:131], v67 offset:30720
	s_waitcnt lgkmcnt(7)
	v_pk_fma_f32 v[148:149], v[100:101], v[40:41], v[148:149]
	v_pk_fma_f32 v[148:149], v[102:103], v[38:39], v[148:149]
	s_waitcnt lgkmcnt(6)
	v_pk_fma_f32 v[150:151], v[104:105], v[40:41], v[150:151]
	v_pk_fma_f32 v[150:151], v[106:107], v[38:39], v[150:151]
	ds_read_b128 v[100:103], v67 offset:34816
	s_waitcnt lgkmcnt(6)
	v_pk_fma_f32 v[152:153], v[108:109], v[40:41], v[152:153]
	v_pk_fma_f32 v[152:153], v[110:111], v[38:39], v[152:153]
	ds_read_b128 v[104:107], v67 offset:38912
	s_waitcnt lgkmcnt(6)
	v_pk_fma_f32 v[154:155], v[112:113], v[40:41], v[154:155]
	v_pk_fma_f32 v[154:155], v[114:115], v[38:39], v[154:155]
	ds_read_b128 v[108:111], v67 offset:43008
	s_waitcnt lgkmcnt(6)
	v_pk_fma_f32 v[156:157], v[116:117], v[40:41], v[156:157]
	v_pk_fma_f32 v[156:157], v[118:119], v[38:39], v[156:157]
	ds_read_b128 v[112:115], v67 offset:47104
	s_waitcnt lgkmcnt(6)
	v_pk_fma_f32 v[158:159], v[120:121], v[40:41], v[158:159]
	v_pk_fma_f32 v[158:159], v[122:123], v[38:39], v[158:159]
	ds_read_b128 v[116:119], v67 offset:51200
	s_waitcnt lgkmcnt(6)
	v_pk_fma_f32 v[160:161], v[124:125], v[40:41], v[160:161]
	v_pk_fma_f32 v[160:161], v[126:127], v[38:39], v[160:161]
	ds_read_b128 v[120:123], v67 offset:55296
	s_waitcnt lgkmcnt(6)
	v_pk_fma_f32 v[162:163], v[128:129], v[40:41], v[162:163]
	v_pk_fma_f32 v[162:163], v[130:131], v[38:39], v[162:163]
	ds_read_b128 v[124:127], v67 offset:59392
	s_waitcnt lgkmcnt(6)
	v_pk_fma_f32 v[164:165], v[100:101], v[40:41], v[164:165]
	v_pk_fma_f32 v[164:165], v[102:103], v[38:39], v[164:165]
	ds_read_b128 v[128:131], v67 offset:63488
	s_waitcnt lgkmcnt(6)
	v_pk_fma_f32 v[168:169], v[104:105], v[40:41], v[168:169]
	v_pk_fma_f32 v[168:169], v[106:107], v[38:39], v[168:169]
	ds_read_b128 v[100:103], v67 offset:3072
	s_waitcnt lgkmcnt(6)
	v_pk_fma_f32 v[170:171], v[108:109], v[40:41], v[170:171]
	v_pk_fma_f32 v[170:171], v[110:111], v[38:39], v[170:171]
	ds_read_b128 v[104:107], v67 offset:7168
	s_waitcnt lgkmcnt(6)
	v_pk_fma_f32 v[172:173], v[112:113], v[40:41], v[172:173]
	v_pk_fma_f32 v[172:173], v[114:115], v[38:39], v[172:173]
	ds_read_b128 v[108:111], v67 offset:11264
	s_waitcnt lgkmcnt(6)
	v_pk_fma_f32 v[174:175], v[116:117], v[40:41], v[174:175]
	v_pk_fma_f32 v[174:175], v[118:119], v[38:39], v[174:175]
	ds_read_b128 v[112:115], v67 offset:15360
	s_waitcnt lgkmcnt(6)
; #define LAS __attribute__((address_space(3)))
; __device__ __forceinline__ unsigned cvt_pk_bf16(float lo, float hi) { unsigned r; asm volatile("v_cvt_pk_bf16_f32 %0, %1, %2" : "=v"(r) : "v"(lo), "v"(hi)); return r; }
; __device__ void phase_norm_alow(const Params& P, int l, int half, LAS unsigned char* lds) {
;     ...
;         for (int i = 0; i < 4; ++i) { f32x4 h = v[i] * r * gv[i];
;             u32x2 w; w.x = cvt_pk_bf16(h[0], h[1]); w.y = cvt_pk_bf16(h[2], h[3]);
;             *(u32x2*)(H + (size_t)row * DM + i * 256 + lane * 4) = w;
; #pragma unroll
;             for (int c = 0; c < 16; ++c) { const f32x4 wv = *(const LAS f32x4*)(WaT + c * 1024 + i * 256 + lane * 4); a[c] += h[0] * wv[0] + h[1] * wv[1] + h[2] * wv[2] + h[3] * wv[3]; } }
;         float b8[8], b4[4], b2[2], b1;
;         { const bool up = (lane & 32) != 0;
; #pragma unroll
;           for (int c = 0; c < 8; ++c) { const float keep = up ? a[c + 8] : a[c], send = up ? a[c] : a[c + 8]; b8[c] = keep + __shfl_xor(send, 32); } }
;         { const bool up = (lane & 16) != 0;
; #pragma unroll
;           for (int c = 0; c < 4; ++c) { const float keep = up ? b8[c + 4] : b8[c], send = up ? b8[c] : b8[c + 4]; b4[c] = keep + __shfl_xor(send, 16); } }
;         { const bool up = (lane & 8) != 0;
; #pragma unroll
;           for (int c = 0; c < 2; ++c) { const float keep = up ? b4[c + 2] : b4[c], send = up ? b4[c] : b4[c + 2]; b2[c] = keep + __shfl_xor(send, 8); } }
;         { const bool up = (lane & 4) != 0; const float keep = up ? b2[1] : b2[0], send = up ? b2[0] : b2[1]; b1 = keep + __shfl_xor(send, 4); }
;         b1 += __shfl_xor(b1, 2); b1 += __shfl_xor(b1, 1);
;         if ((lane & 3) == 0) { const int co = ((lane >> 5) & 1) * 8 + ((lane >> 4) & 1) * 4 + ((lane >> 3) & 1) * 2 + ((lane >> 2) & 1); AL[(size_t)row * 16 + co] = b1; }
	v_pk_fma_f32 v[176:177], v[120:121], v[40:41], v[176:177]
	v_pk_fma_f32 v[176:177], v[122:123], v[38:39], v[176:177]
	ds_read_b128 v[116:119], v67 offset:19456
	s_waitcnt lgkmcnt(6)
	v_pk_fma_f32 v[178:179], v[124:125], v[40:41], v[178:179]
	v_pk_fma_f32 v[178:179], v[126:127], v[38:39], v[178:179]
	ds_read_b128 v[120:123], v67 offset:23552
	s_waitcnt lgkmcnt(6)
	v_pk_fma_f32 v[180:181], v[128:129], v[40:41], v[180:181]
	v_pk_fma_f32 v[180:181], v[130:131], v[38:39], v[180:181]
	v_pk_mul_f32 v[40:41], v[34:35], v[58:59] op_sel_hi:[1,0]
	v_pk_mul_f32 v[34:35], v[36:37], v[58:59] op_sel_hi:[1,0]
	v_pk_mul_f32 v[36:37], v[2:3], v[40:41]
	v_pk_mul_f32 v[34:35], v[4:5], v[34:35]
	v_cvt_pk_bf16_f32 v40, v36, v37
	s_nop 0
	v_cvt_pk_bf16_f32 v41, v34, v35
	ds_read_b128 v[124:127], v67 offset:27648
	global_store_dwordx2 v[46:47], v[40:41], off offset:1536
	s_waitcnt lgkmcnt(6)
	v_pk_fma_f32 v[148:149], v[100:101], v[36:37], v[148:149]
	v_pk_fma_f32 v[148:149], v[102:103], v[34:35], v[148:149]
	ds_read_b128 v[128:131], v67 offset:31744
	v_add_f32_e32 v39, v148, v149
	s_waitcnt lgkmcnt(6)
	v_pk_fma_f32 v[150:151], v[104:105], v[36:37], v[150:151]
	v_pk_fma_f32 v[150:151], v[106:107], v[34:35], v[150:151]
	ds_read_b128 v[100:103], v67 offset:35840
	v_add_f32_e32 v40, v150, v151
	s_waitcnt lgkmcnt(6)
	v_pk_fma_f32 v[152:153], v[108:109], v[36:37], v[152:153]
	v_pk_fma_f32 v[152:153], v[110:111], v[34:35], v[152:153]
	ds_read_b128 v[104:107], v67 offset:39936
	v_add_f32_e32 v41, v152, v153
	s_waitcnt lgkmcnt(6)
	v_pk_fma_f32 v[154:155], v[112:113], v[36:37], v[154:155]
	v_pk_fma_f32 v[154:155], v[114:115], v[34:35], v[154:155]
	v_add_f32_e32 v42, v154, v155
	ds_read_b128 v[108:111], v67 offset:44032
	s_waitcnt lgkmcnt(6)
	v_pk_fma_f32 v[156:157], v[116:117], v[36:37], v[156:157]
	v_pk_fma_f32 v[156:157], v[118:119], v[34:35], v[156:157]
	ds_read_b128 v[112:115], v67 offset:48128
	v_add_f32_e32 v43, v156, v157
	s_waitcnt lgkmcnt(6)
	v_pk_fma_f32 v[158:159], v[120:121], v[36:37], v[158:159]
	v_pk_fma_f32 v[158:159], v[122:123], v[34:35], v[158:159]
	v_add_f32_e32 v48, v158, v159
	ds_read_b128 v[116:119], v67 offset:52224
	s_waitcnt lgkmcnt(6)
	v_pk_fma_f32 v[160:161], v[124:125], v[36:37], v[160:161]
	v_pk_fma_f32 v[160:161], v[126:127], v[34:35], v[160:161]
	v_add_f32_e32 v49, v160, v161
	ds_read_b128 v[120:123], v67 offset:56320
	s_waitcnt lgkmcnt(6)
	v_pk_fma_f32 v[162:163], v[128:129], v[36:37], v[162:163]
	v_pk_fma_f32 v[162:163], v[130:131], v[34:35], v[162:163]
	v_add_f32_e32 v51, v162, v163
	ds_read_b128 v[124:127], v67 offset:60416
	s_waitcnt lgkmcnt(6)
	v_pk_fma_f32 v[164:165], v[100:101], v[36:37], v[164:165]
	v_pk_fma_f32 v[164:165], v[102:103], v[34:35], v[164:165]
	v_add_f32_e32 v58, v164, v165
	ds_read_b128 v[128:131], v67 offset:64512
	s_waitcnt lgkmcnt(6)
	v_pk_fma_f32 v[168:169], v[104:105], v[36:37], v[168:169]
	v_pk_fma_f32 v[168:169], v[106:107], v[34:35], v[168:169]
	v_add_f32_e32 v60, v168, v169
	s_waitcnt lgkmcnt(5)
	v_pk_fma_f32 v[170:171], v[108:109], v[36:37], v[170:171]
	v_pk_fma_f32 v[170:171], v[110:111], v[34:35], v[170:171]
	v_add_f32_e32 v61, v170, v171
	s_waitcnt lgkmcnt(4)
	v_pk_fma_f32 v[172:173], v[112:113], v[36:37], v[172:173]
	v_pk_fma_f32 v[172:173], v[114:115], v[34:35], v[172:173]
	v_add_f32_e32 v68, v172, v173
	s_waitcnt lgkmcnt(3)
	v_pk_fma_f32 v[174:175], v[116:117], v[36:37], v[174:175]
	v_pk_fma_f32 v[174:175], v[118:119], v[34:35], v[174:175]
	v_add_f32_e32 v69, v174, v175
	s_waitcnt lgkmcnt(2)
	v_pk_fma_f32 v[176:177], v[120:121], v[36:37], v[176:177]
	v_pk_fma_f32 v[176:177], v[122:123], v[34:35], v[176:177]
	v_add_f32_e32 v70, v176, v177
	s_waitcnt lgkmcnt(1)
	v_pk_fma_f32 v[178:179], v[124:125], v[36:37], v[178:179]
	v_pk_fma_f32 v[178:179], v[126:127], v[34:35], v[178:179]
	v_add_f32_e32 v71, v178, v179
	s_waitcnt lgkmcnt(0)
	v_pk_fma_f32 v[180:181], v[128:129], v[36:37], v[180:181]
	v_pk_fma_f32 v[180:181], v[130:131], v[34:35], v[180:181]
	v_cndmask_b32_e32 v36, v39, v58, vcc
	v_add_f32_e32 v34, v180, v181
	ds_bpermute_b32 v36, v59, v36
	v_cndmask_b32_e32 v37, v40, v60, vcc
	ds_bpermute_b32 v37, v59, v37
	v_cndmask_b32_e32 v38, v41, v61, vcc
	ds_bpermute_b32 v38, v59, v38
	v_cndmask_b32_e32 v35, v58, v39, vcc
	v_cndmask_b32_e32 v39, v42, v68, vcc
	s_waitcnt lgkmcnt(2)
	v_add_f32_e32 v35, v35, v36
	v_cndmask_b32_e32 v36, v60, v40, vcc
	ds_bpermute_b32 v39, v59, v39
	v_cndmask_b32_e32 v40, v43, v69, vcc
	s_waitcnt lgkmcnt(2)
	v_add_f32_e32 v36, v36, v37
	v_cndmask_b32_e32 v37, v61, v41, vcc
	ds_bpermute_b32 v40, v59, v40
	v_cndmask_b32_e32 v41, v48, v70, vcc
	s_waitcnt lgkmcnt(2)
	v_add_f32_e32 v37, v37, v38
	v_cndmask_b32_e32 v38, v68, v42, vcc
	ds_bpermute_b32 v41, v59, v41
	v_cndmask_b32_e32 v42, v49, v71, vcc
	ds_bpermute_b32 v42, v59, v42
	s_waitcnt lgkmcnt(3)
	v_add_f32_e32 v38, v38, v39
	v_cndmask_b32_e32 v39, v69, v43, vcc
	s_waitcnt lgkmcnt(2)
	v_add_f32_e32 v39, v39, v40
	v_cndmask_b32_e32 v40, v70, v48, vcc
	s_waitcnt lgkmcnt(1)
	v_add_f32_e32 v40, v40, v41
	v_cndmask_b32_e32 v41, v71, v49, vcc
	s_waitcnt lgkmcnt(0)
	v_add_f32_e32 v41, v41, v42
	v_cndmask_b32_e32 v42, v34, v51, vcc
	v_cndmask_b32_e32 v34, v51, v34, vcc
	ds_bpermute_b32 v34, v59, v34
	s_waitcnt lgkmcnt(0)
	v_add_f32_e32 v34, v42, v34
	v_cndmask_b32_e64 v42, v39, v35, s[36:37]
	v_cndmask_b32_e64 v35, v35, v39, s[36:37]
	v_cndmask_b32_e64 v39, v40, v36, s[36:37]
	v_cndmask_b32_e64 v36, v36, v40, s[36:37]
	ds_bpermute_b32 v36, v62, v36
	ds_bpermute_b32 v35, v62, v35
	s_waitcnt lgkmcnt(1)
	v_add_f32_e32 v36, v39, v36
	v_cndmask_b32_e64 v39, v41, v37, s[36:37]
	v_cndmask_b32_e64 v37, v37, v41, s[36:37]
	ds_bpermute_b32 v37, v62, v37
	s_waitcnt lgkmcnt(1)
	v_add_f32_e32 v35, v42, v35
	s_waitcnt lgkmcnt(0)
	v_add_f32_e32 v37, v39, v37
	v_cndmask_b32_e64 v39, v34, v38, s[36:37]
	v_cndmask_b32_e64 v34, v38, v34, s[36:37]
	ds_bpermute_b32 v34, v62, v34
	v_cndmask_b32_e64 v38, v37, v35, s[38:39]
	v_cndmask_b32_e64 v35, v35, v37, s[38:39]
	ds_bpermute_b32 v35, v63, v35
	s_waitcnt lgkmcnt(1)
	v_add_f32_e32 v34, v39, v34
	v_cndmask_b32_e64 v37, v34, v36, s[38:39]
	v_cndmask_b32_e64 v34, v36, v34, s[38:39]
	ds_bpermute_b32 v34, v63, v34
	s_waitcnt lgkmcnt(1)
	v_add_f32_e32 v35, v38, v35
	s_waitcnt lgkmcnt(0)
	v_add_f32_e32 v34, v37, v34
	v_cndmask_b32_e64 v36, v34, v35, s[40:41]
	v_cndmask_b32_e64 v34, v35, v34, s[40:41]
	ds_bpermute_b32 v34, v64, v34
	s_waitcnt lgkmcnt(0)
	v_add_f32_e32 v34, v36, v34
	s_nop 1
	v_mov_b32_dpp v35, v34 quad_perm:[2,3,0,1] row_mask:0xf bank_mask:0xf
	s_waitcnt lgkmcnt(0)
	v_add_f32_e32 v34, v34, v35
	s_nop 1
	v_mov_b32_dpp v35, v34 quad_perm:[1,0,3,2] row_mask:0xf bank_mask:0xf
	s_and_saveexec_b64 s[0:1], s[42:43]
	s_cbranch_execz .LBB0_117
	v_lshl_add_u64 v[36:37], s[74:75], 0, v[54:55]
	s_waitcnt lgkmcnt(0)
	v_add_f32_e32 v34, v34, v35
	global_store_dword v[36:37], v34, off
	s_branch .LBB0_117

; #define LAS __attribute__((address_space(3)))
; __device__ __forceinline__ unsigned cvt_pk_bf16(float lo, float hi) { unsigned r; asm volatile("v_cvt_pk_bf16_f32 %0, %1, %2" : "=v"(r) : "v"(lo), "v"(hi)); return r; }
; __device__ void phase_norm_alow(const Params& P, int l, int half, LAS unsigned char* lds) {
;     ...
;         for (int i = 0; i < 4; ++i) { v[i] = nv[i]; ss += v[i][0] * v[i][0] + v[i][1] * v[i][1] + v[i][2] * v[i][2] + v[i][3] * v[i][3]; }
;         if (row + rstride < TH) {
; #pragma unroll
;             for (int i = 0; i < 4; ++i) nv[i] = *(const f32x4*)(xs + (size_t)(row + rstride) * DM + i * 256 + lane * 4);
;         }
;         ss = wave_sum(ss);
;         const float r = rsqrtf(ss * (1.0f / DM) + EPS);
;         float a[16];
; #pragma unroll
;         for (int c = 0; c < 16; ++c) a[c] = 0.f;
; #pragma unroll
;         for (int i = 0; i < 4; ++i) { f32x4 h = v[i] * r * gv[i];
;             u32x2 w; w.x = cvt_pk_bf16(h[0], h[1]); w.y = cvt_pk_bf16(h[2], h[3]);
;             *(u32x2*)(H + (size_t)row * DM + i * 256 + lane * 4) = w;
; #pragma unroll
;             for (int c = 0; c < 16; ++c) { const f32x4 wv = *(const LAS f32x4*)(WaT + c * 1024 + i * 256 + lane * 4); a[c] += h[0] * wv[0] + h[1] * wv[1] + h[2] * wv[2] + h[3] * wv[3]; } }
.LBB0_242:
	s_or_b64 exec, exec, s[30:31]
	v_mul_f32_e32 v51, v47, v47
	v_mul_f32_e32 v58, v43, v43
	v_fmac_f32_e32 v51, v46, v46
	v_fmac_f32_e32 v58, v42, v42
	v_fmac_f32_e32 v51, v48, v48
	v_fmac_f32_e32 v58, v44, v44
	v_fmac_f32_e32 v51, v49, v49
	v_fmac_f32_e32 v58, v45, v45
	v_add_f32_e32 v51, v51, v58
	v_mul_f32_e32 v58, v39, v39
	v_fmac_f32_e32 v58, v38, v38
	v_fmac_f32_e32 v58, v40, v40
	v_fmac_f32_e32 v58, v41, v41
	v_add_f32_e32 v51, v51, v58
	v_mul_f32_e32 v58, v35, v35
	v_fmac_f32_e32 v58, v34, v34
	v_fmac_f32_e32 v58, v36, v36
	v_fmac_f32_e32 v58, v37, v37
	v_add_f32_e32 v51, v51, v58
	v_mov_b32_e32 v58, v51
	s_nop 1
	v_permlane32_swap_b32_e32 v58, v51
	s_nop 1
	v_lshl_add_u64 v[68:69], s[74:75], 0, v[54:55]
	s_waitcnt lgkmcnt(0)
	v_add_f32_e32 v51, v51, v58
	v_mov_b32_e32 v58, v51
	s_nop 1
	v_permlane16_swap_b32_e32 v58, v51
	s_nop 1
	s_waitcnt lgkmcnt(0)
	v_add_f32_e32 v51, v51, v58
	s_nop 1
	v_mov_b32_dpp v58, v51 row_ror:8 row_mask:0xf bank_mask:0xf
	s_waitcnt lgkmcnt(0)
	v_add_f32_e32 v51, v51, v58
	s_nop 1
	v_mov_b32_dpp v58, v51 row_shl:4 row_mask:0xf bank_mask:0x5
	s_nop 1
	v_mov_b32_dpp v58, v51 row_shr:4 row_mask:0xf bank_mask:0xa
	s_waitcnt lgkmcnt(0)
	v_add_f32_e32 v51, v51, v58
	s_nop 1
	v_mov_b32_dpp v58, v51 quad_perm:[2,3,0,1] row_mask:0xf bank_mask:0xf
	s_waitcnt lgkmcnt(0)
	v_add_f32_e32 v51, v51, v58
	s_nop 1
	v_mov_b32_dpp v58, v51 quad_perm:[1,0,3,2] row_mask:0xf bank_mask:0xf
	s_waitcnt lgkmcnt(0)
	v_add_f32_e32 v51, v51, v58
	v_fmamk_f32 v51, v51, 0x3a800000, v1
	v_cmp_gt_f32_e64 s[0:1], s33, v51
	v_mul_f32_e32 v58, 0x4b800000, v51
	s_nop 0
	v_cndmask_b32_e64 v51, v51, v58, s[0:1]
	v_rsq_f32_e32 v51, v51
	s_nop 0
	v_mul_f32_e32 v58, 0x45800000, v51
	v_cndmask_b32_e64 v58, v51, v58, s[0:1]
	v_pk_mul_f32 v[46:47], v[46:47], v[58:59] op_sel_hi:[1,0]
	s_mov_b32 s0, 0x5a88000
	v_pk_mul_f32 v[48:49], v[48:49], v[58:59] op_sel_hi:[1,0]
	v_pk_mul_f32 v[60:61], v[14:15], v[46:47]
	v_add_co_u32_e64 v46, s[0:1], s0, v68
	v_pk_mul_f32 v[48:49], v[16:17], v[48:49]
	v_cvt_pk_bf16_f32 v70, v60, v61
	s_nop 0
	v_addc_co_u32_e64 v47, s[0:1], 0, v69, s[0:1]
	v_cvt_pk_bf16_f32 v71, v48, v49
	global_store_dwordx2 v[46:47], v[70:71], off
	ds_read_b128 v[100:103], v67
	ds_read_b128 v[104:107], v67 offset:4096
	ds_read_b128 v[108:111], v67 offset:8192
	ds_read_b128 v[112:115], v67 offset:12288
	ds_read_b128 v[116:119], v67 offset:16384
	ds_read_b128 v[120:123], v67 offset:20480
	ds_read_b128 v[124:127], v67 offset:24576
	s_waitcnt lgkmcnt(6)
	v_pk_mul_f32 v[148:149], v[100:101], v[60:61]
	v_pk_fma_f32 v[148:149], v[102:103], v[48:49], v[148:149]
	ds_read_b128 v[128:131], v67 offset:28672
	s_waitcnt lgkmcnt(6)
	v_pk_mul_f32 v[150:151], v[104:105], v[60:61]
	v_pk_fma_f32 v[150:151], v[106:107], v[48:49], v[150:151]
	ds_read_b128 v[100:103], v67 offset:32768
	s_waitcnt lgkmcnt(6)
	v_pk_mul_f32 v[152:153], v[108:109], v[60:61]
	v_pk_fma_f32 v[152:153], v[110:111], v[48:49], v[152:153]
	ds_read_b128 v[104:107], v67 offset:36864
	s_waitcnt lgkmcnt(6)
	v_pk_mul_f32 v[154:155], v[112:113], v[60:61]
	v_pk_fma_f32 v[154:155], v[114:115], v[48:49], v[154:155]
	ds_read_b128 v[108:111], v67 offset:40960
	s_waitcnt lgkmcnt(6)
	v_pk_mul_f32 v[156:157], v[116:117], v[60:61]
	v_pk_fma_f32 v[156:157], v[118:119], v[48:49], v[156:157]
	ds_read_b128 v[112:115], v67 offset:45056
	s_waitcnt lgkmcnt(6)
	v_pk_mul_f32 v[158:159], v[120:121], v[60:61]
	v_pk_fma_f32 v[158:159], v[122:123], v[48:49], v[158:159]
	ds_read_b128 v[116:119], v67 offset:49152
	s_waitcnt lgkmcnt(6)
	v_pk_mul_f32 v[160:161], v[124:125], v[60:61]
	v_pk_fma_f32 v[160:161], v[126:127], v[48:49], v[160:161]
	ds_read_b128 v[120:123], v67 offset:53248
	s_waitcnt lgkmcnt(6)
	v_pk_mul_f32 v[162:163], v[128:129], v[60:61]
	v_pk_fma_f32 v[162:163], v[130:131], v[48:49], v[162:163]
	ds_read_b128 v[124:127], v67 offset:57344
	s_waitcnt lgkmcnt(6)
	v_pk_mul_f32 v[164:165], v[100:101], v[60:61]
	v_pk_fma_f32 v[164:165], v[102:103], v[48:49], v[164:165]
	ds_read_b128 v[128:131], v67 offset:61440
	s_waitcnt lgkmcnt(6)
	v_pk_mul_f32 v[168:169], v[104:105], v[60:61]
	v_pk_fma_f32 v[168:169], v[106:107], v[48:49], v[168:169]
	ds_read_b128 v[100:103], v67 offset:1024
	s_waitcnt lgkmcnt(6)
	v_pk_mul_f32 v[170:171], v[108:109], v[60:61]
	v_pk_fma_f32 v[170:171], v[110:111], v[48:49], v[170:171]
	ds_read_b128 v[104:107], v67 offset:5120
	s_waitcnt lgkmcnt(6)
	v_pk_mul_f32 v[172:173], v[112:113], v[60:61]
	v_pk_fma_f32 v[172:173], v[114:115], v[48:49], v[172:173]
	ds_read_b128 v[108:111], v67 offset:9216
	s_waitcnt lgkmcnt(6)
	v_pk_mul_f32 v[174:175], v[116:117], v[60:61]
	v_pk_fma_f32 v[174:175], v[118:119], v[48:49], v[174:175]
	ds_read_b128 v[112:115], v67 offset:13312
	s_waitcnt lgkmcnt(6)
	v_pk_mul_f32 v[176:177], v[120:121], v[60:61]
	v_pk_fma_f32 v[176:177], v[122:123], v[48:49], v[176:177]
	ds_read_b128 v[116:119], v67 offset:17408
	s_waitcnt lgkmcnt(6)
	v_pk_mul_f32 v[178:179], v[124:125], v[60:61]
	v_pk_fma_f32 v[178:179], v[126:127], v[48:49], v[178:179]
	ds_read_b128 v[120:123], v67 offset:21504
	s_waitcnt lgkmcnt(6)
	v_pk_mul_f32 v[180:181], v[128:129], v[60:61]
	v_pk_fma_f32 v[180:181], v[130:131], v[48:49], v[180:181]
	v_pk_mul_f32 v[60:61], v[42:43], v[58:59] op_sel_hi:[1,0]
	v_pk_mul_f32 v[42:43], v[44:45], v[58:59] op_sel_hi:[1,0]
	v_pk_mul_f32 v[44:45], v[10:11], v[60:61]
	v_pk_mul_f32 v[42:43], v[12:13], v[42:43]
	v_cvt_pk_bf16_f32 v60, v44, v45
	s_nop 0
	v_cvt_pk_bf16_f32 v61, v42, v43
	ds_read_b128 v[124:127], v67 offset:25600
	global_store_dwordx2 v[46:47], v[60:61], off offset:512
	s_waitcnt lgkmcnt(6)
; #define LAS __attribute__((address_space(3)))
; __device__ __forceinline__ unsigned cvt_pk_bf16(float lo, float hi) { unsigned r; asm volatile("v_cvt_pk_bf16_f32 %0, %1, %2" : "=v"(r) : "v"(lo), "v"(hi)); return r; }
; __device__ void phase_norm_alow(const Params& P, int l, int half, LAS unsigned char* lds) {
;     ...
;         for (int i = 0; i < 4; ++i) { f32x4 h = v[i] * r * gv[i];
;             u32x2 w; w.x = cvt_pk_bf16(h[0], h[1]); w.y = cvt_pk_bf16(h[2], h[3]);
;             *(u32x2*)(H + (size_t)row * DM + i * 256 + lane * 4) = w;
; #pragma unroll
;             for (int c = 0; c < 16; ++c) { const f32x4 wv = *(const LAS f32x4*)(WaT + c * 1024 + i * 256 + lane * 4); a[c] += h[0] * wv[0] + h[1] * wv[1] + h[2] * wv[2] + h[3] * wv[3]; } }
	v_pk_fma_f32 v[148:149], v[100:101], v[44:45], v[148:149]
	v_pk_fma_f32 v[148:149], v[102:103], v[42:43], v[148:149]
	ds_read_b128 v[128:131], v67 offset:29696
	s_waitcnt lgkmcnt(6)
	v_pk_fma_f32 v[150:151], v[104:105], v[44:45], v[150:151]
	v_pk_fma_f32 v[150:151], v[106:107], v[42:43], v[150:151]
	ds_read_b128 v[100:103], v67 offset:33792
	s_waitcnt lgkmcnt(6)
	v_pk_fma_f32 v[152:153], v[108:109], v[44:45], v[152:153]
	v_pk_fma_f32 v[152:153], v[110:111], v[42:43], v[152:153]
	ds_read_b128 v[104:107], v67 offset:37888
	s_waitcnt lgkmcnt(6)
	v_pk_fma_f32 v[154:155], v[112:113], v[44:45], v[154:155]
	v_pk_fma_f32 v[154:155], v[114:115], v[42:43], v[154:155]
	ds_read_b128 v[108:111], v67 offset:41984
	s_waitcnt lgkmcnt(6)
	v_pk_fma_f32 v[156:157], v[116:117], v[44:45], v[156:157]
	v_pk_fma_f32 v[156:157], v[118:119], v[42:43], v[156:157]
	ds_read_b128 v[112:115], v67 offset:46080
	s_waitcnt lgkmcnt(6)
	v_pk_fma_f32 v[158:159], v[120:121], v[44:45], v[158:159]
	v_pk_fma_f32 v[158:159], v[122:123], v[42:43], v[158:159]
	ds_read_b128 v[116:119], v67 offset:50176
	s_waitcnt lgkmcnt(6)
	v_pk_fma_f32 v[160:161], v[124:125], v[44:45], v[160:161]
	v_pk_fma_f32 v[160:161], v[126:127], v[42:43], v[160:161]
	ds_read_b128 v[120:123], v67 offset:54272
	s_waitcnt lgkmcnt(6)
	v_pk_fma_f32 v[162:163], v[128:129], v[44:45], v[162:163]
	v_pk_fma_f32 v[162:163], v[130:131], v[42:43], v[162:163]
	ds_read_b128 v[124:127], v67 offset:58368
	s_waitcnt lgkmcnt(6)
	v_pk_fma_f32 v[164:165], v[100:101], v[44:45], v[164:165]
	v_pk_fma_f32 v[164:165], v[102:103], v[42:43], v[164:165]
	ds_read_b128 v[128:131], v67 offset:62464
	s_waitcnt lgkmcnt(6)
	v_pk_fma_f32 v[168:169], v[104:105], v[44:45], v[168:169]
	v_pk_fma_f32 v[168:169], v[106:107], v[42:43], v[168:169]
	ds_read_b128 v[100:103], v67 offset:2048
	s_waitcnt lgkmcnt(6)
	v_pk_fma_f32 v[170:171], v[108:109], v[44:45], v[170:171]
	v_pk_fma_f32 v[170:171], v[110:111], v[42:43], v[170:171]
	ds_read_b128 v[104:107], v67 offset:6144
	s_waitcnt lgkmcnt(6)
	v_pk_fma_f32 v[172:173], v[112:113], v[44:45], v[172:173]
	v_pk_fma_f32 v[172:173], v[114:115], v[42:43], v[172:173]
	ds_read_b128 v[108:111], v67 offset:10240
	s_waitcnt lgkmcnt(6)
	v_pk_fma_f32 v[174:175], v[116:117], v[44:45], v[174:175]
	v_pk_fma_f32 v[174:175], v[118:119], v[42:43], v[174:175]
	ds_read_b128 v[112:115], v67 offset:14336
	s_waitcnt lgkmcnt(6)
	v_pk_fma_f32 v[176:177], v[120:121], v[44:45], v[176:177]
	v_pk_fma_f32 v[176:177], v[122:123], v[42:43], v[176:177]
	ds_read_b128 v[116:119], v67 offset:18432
	s_waitcnt lgkmcnt(6)
	v_pk_fma_f32 v[178:179], v[124:125], v[44:45], v[178:179]
	v_pk_fma_f32 v[178:179], v[126:127], v[42:43], v[178:179]
	ds_read_b128 v[120:123], v67 offset:22528
	s_waitcnt lgkmcnt(6)
	v_pk_fma_f32 v[180:181], v[128:129], v[44:45], v[180:181]
	v_pk_fma_f32 v[180:181], v[130:131], v[42:43], v[180:181]
	v_pk_mul_f32 v[42:43], v[38:39], v[58:59] op_sel_hi:[1,0]
	v_pk_mul_f32 v[38:39], v[40:41], v[58:59] op_sel_hi:[1,0]
	v_pk_mul_f32 v[40:41], v[6:7], v[42:43]
	v_pk_mul_f32 v[38:39], v[8:9], v[38:39]
	v_cvt_pk_bf16_f32 v42, v40, v41
	v_cvt_pk_bf16_f32 v43, v38, v39
	global_store_dwordx2 v[46:47], v[42:43], off offset:1024
	ds_read_b128 v[124:127], v67 offset:26624
	ds_read_b128 v[128:131], v67 offset:30720
	s_waitcnt lgkmcnt(7)
	v_pk_fma_f32 v[148:149], v[100:101], v[40:41], v[148:149]
	v_pk_fma_f32 v[148:149], v[102:103], v[38:39], v[148:149]
	s_waitcnt lgkmcnt(6)
	v_pk_fma_f32 v[150:151], v[104:105], v[40:41], v[150:151]
	v_pk_fma_f32 v[150:151], v[106:107], v[38:39], v[150:151]
	ds_read_b128 v[100:103], v67 offset:34816
	s_waitcnt lgkmcnt(6)
	v_pk_fma_f32 v[152:153], v[108:109], v[40:41], v[152:153]
	v_pk_fma_f32 v[152:153], v[110:111], v[38:39], v[152:153]
	ds_read_b128 v[104:107], v67 offset:38912
	s_waitcnt lgkmcnt(6)
	v_pk_fma_f32 v[154:155], v[112:113], v[40:41], v[154:155]
	v_pk_fma_f32 v[154:155], v[114:115], v[38:39], v[154:155]
	ds_read_b128 v[108:111], v67 offset:43008
	s_waitcnt lgkmcnt(6)
	v_pk_fma_f32 v[156:157], v[116:117], v[40:41], v[156:157]
	v_pk_fma_f32 v[156:157], v[118:119], v[38:39], v[156:157]
	ds_read_b128 v[112:115], v67 offset:47104
	s_waitcnt lgkmcnt(6)
	v_pk_fma_f32 v[158:159], v[120:121], v[40:41], v[158:159]
	v_pk_fma_f32 v[158:159], v[122:123], v[38:39], v[158:159]
	ds_read_b128 v[116:119], v67 offset:51200
	s_waitcnt lgkmcnt(6)
	v_pk_fma_f32 v[160:161], v[124:125], v[40:41], v[160:161]
	v_pk_fma_f32 v[160:161], v[126:127], v[38:39], v[160:161]
	ds_read_b128 v[120:123], v67 offset:55296
	s_waitcnt lgkmcnt(6)
	v_pk_fma_f32 v[162:163], v[128:129], v[40:41], v[162:163]
	v_pk_fma_f32 v[162:163], v[130:131], v[38:39], v[162:163]
	ds_read_b128 v[124:127], v67 offset:59392
	s_waitcnt lgkmcnt(6)
	v_pk_fma_f32 v[164:165], v[100:101], v[40:41], v[164:165]
	v_pk_fma_f32 v[164:165], v[102:103], v[38:39], v[164:165]
	ds_read_b128 v[128:131], v67 offset:63488
	s_waitcnt lgkmcnt(6)
	v_pk_fma_f32 v[168:169], v[104:105], v[40:41], v[168:169]
	v_pk_fma_f32 v[168:169], v[106:107], v[38:39], v[168:169]
	ds_read_b128 v[100:103], v67 offset:3072
	s_waitcnt lgkmcnt(6)
	v_pk_fma_f32 v[170:171], v[108:109], v[40:41], v[170:171]
	v_pk_fma_f32 v[170:171], v[110:111], v[38:39], v[170:171]
	ds_read_b128 v[104:107], v67 offset:7168
	s_waitcnt lgkmcnt(6)
	v_pk_fma_f32 v[172:173], v[112:113], v[40:41], v[172:173]
	v_pk_fma_f32 v[172:173], v[114:115], v[38:39], v[172:173]
	ds_read_b128 v[108:111], v67 offset:11264
	s_waitcnt lgkmcnt(6)
	v_pk_fma_f32 v[174:175], v[116:117], v[40:41], v[174:175]
	v_pk_fma_f32 v[174:175], v[118:119], v[38:39], v[174:175]
	ds_read_b128 v[112:115], v67 offset:15360
	s_waitcnt lgkmcnt(6)
; #define LAS __attribute__((address_space(3)))
; __device__ __forceinline__ unsigned cvt_pk_bf16(float lo, float hi) { unsigned r; asm volatile("v_cvt_pk_bf16_f32 %0, %1, %2" : "=v"(r) : "v"(lo), "v"(hi)); return r; }
; __device__ void phase_norm_alow(const Params& P, int l, int half, LAS unsigned char* lds) {
;     ...
;         for (int i = 0; i < 4; ++i) { f32x4 h = v[i] * r * gv[i];
;             u32x2 w; w.x = cvt_pk_bf16(h[0], h[1]); w.y = cvt_pk_bf16(h[2], h[3]);
;             *(u32x2*)(H + (size_t)row * DM + i * 256 + lane * 4) = w;
; #pragma unroll
;             for (int c = 0; c < 16; ++c) { const f32x4 wv = *(const LAS f32x4*)(WaT + c * 1024 + i * 256 + lane * 4); a[c] += h[0] * wv[0] + h[1] * wv[1] + h[2] * wv[2] + h[3] * wv[3]; } }
;         float b8[8], b4[4], b2[2], b1;
;         { const bool up = (lane & 32) != 0;
; #pragma unroll
;           for (int c = 0; c < 8; ++c) { const float keep = up ? a[c + 8] : a[c], send = up ? a[c] : a[c + 8]; b8[c] = keep + __shfl_xor(send, 32); } }
;         { const bool up = (lane & 16) != 0;
; #pragma unroll
;           for (int c = 0; c < 4; ++c) { const float keep = up ? b8[c + 4] : b8[c], send = up ? b8[c] : b8[c + 4]; b4[c] = keep + __shfl_xor(send, 16); } }
;         { const bool up = (lane & 8) != 0;
; #pragma unroll
;           for (int c = 0; c < 2; ++c) { const float keep = up ? b4[c + 2] : b4[c], send = up ? b4[c] : b4[c + 2]; b2[c] = keep + __shfl_xor(send, 8); } }
;         { const bool up = (lane & 4) != 0; const float keep = up ? b2[1] : b2[0], send = up ? b2[0] : b2[1]; b1 = keep + __shfl_xor(send, 4); }
;         b1 += __shfl_xor(b1, 2); b1 += __shfl_xor(b1, 1);
;         if ((lane & 3) == 0) { const int co = ((lane >> 5) & 1) * 8 + ((lane >> 4) & 1) * 4 + ((lane >> 3) & 1) * 2 + ((lane >> 2) & 1); AL[(size_t)row * 16 + co] = b1; }
	v_pk_fma_f32 v[176:177], v[120:121], v[40:41], v[176:177]
	v_pk_fma_f32 v[176:177], v[122:123], v[38:39], v[176:177]
	ds_read_b128 v[116:119], v67 offset:19456
	s_waitcnt lgkmcnt(6)
	v_pk_fma_f32 v[178:179], v[124:125], v[40:41], v[178:179]
	v_pk_fma_f32 v[178:179], v[126:127], v[38:39], v[178:179]
	ds_read_b128 v[120:123], v67 offset:23552
	s_waitcnt lgkmcnt(6)
	v_pk_fma_f32 v[180:181], v[128:129], v[40:41], v[180:181]
	v_pk_fma_f32 v[180:181], v[130:131], v[38:39], v[180:181]
	v_pk_mul_f32 v[40:41], v[34:35], v[58:59] op_sel_hi:[1,0]
	v_pk_mul_f32 v[34:35], v[36:37], v[58:59] op_sel_hi:[1,0]
	v_pk_mul_f32 v[36:37], v[2:3], v[40:41]
	v_pk_mul_f32 v[34:35], v[4:5], v[34:35]
	v_cvt_pk_bf16_f32 v40, v36, v37
	s_nop 0
	v_cvt_pk_bf16_f32 v41, v34, v35
	ds_read_b128 v[124:127], v67 offset:27648
	global_store_dwordx2 v[46:47], v[40:41], off offset:1536
	s_waitcnt lgkmcnt(6)
	v_pk_fma_f32 v[148:149], v[100:101], v[36:37], v[148:149]
	v_pk_fma_f32 v[148:149], v[102:103], v[34:35], v[148:149]
	ds_read_b128 v[128:131], v67 offset:31744
	v_add_f32_e32 v39, v148, v149
	s_waitcnt lgkmcnt(6)
	v_pk_fma_f32 v[150:151], v[104:105], v[36:37], v[150:151]
	v_pk_fma_f32 v[150:151], v[106:107], v[34:35], v[150:151]
	ds_read_b128 v[100:103], v67 offset:35840
	v_add_f32_e32 v40, v150, v151
	s_waitcnt lgkmcnt(6)
	v_pk_fma_f32 v[152:153], v[108:109], v[36:37], v[152:153]
	v_pk_fma_f32 v[152:153], v[110:111], v[34:35], v[152:153]
	ds_read_b128 v[104:107], v67 offset:39936
	v_add_f32_e32 v41, v152, v153
	s_waitcnt lgkmcnt(6)
	v_pk_fma_f32 v[154:155], v[112:113], v[36:37], v[154:155]
	v_pk_fma_f32 v[154:155], v[114:115], v[34:35], v[154:155]
	v_add_f32_e32 v42, v154, v155
	ds_read_b128 v[108:111], v67 offset:44032
	s_waitcnt lgkmcnt(6)
	v_pk_fma_f32 v[156:157], v[116:117], v[36:37], v[156:157]
	v_pk_fma_f32 v[156:157], v[118:119], v[34:35], v[156:157]
	ds_read_b128 v[112:115], v67 offset:48128
	v_add_f32_e32 v43, v156, v157
	s_waitcnt lgkmcnt(6)
	v_pk_fma_f32 v[158:159], v[120:121], v[36:37], v[158:159]
	v_pk_fma_f32 v[158:159], v[122:123], v[34:35], v[158:159]
	v_add_f32_e32 v48, v158, v159
	ds_read_b128 v[116:119], v67 offset:52224
	s_waitcnt lgkmcnt(6)
	v_pk_fma_f32 v[160:161], v[124:125], v[36:37], v[160:161]
	v_pk_fma_f32 v[160:161], v[126:127], v[34:35], v[160:161]
	v_add_f32_e32 v49, v160, v161
	ds_read_b128 v[120:123], v67 offset:56320
	s_waitcnt lgkmcnt(6)
	v_pk_fma_f32 v[162:163], v[128:129], v[36:37], v[162:163]
	v_pk_fma_f32 v[162:163], v[130:131], v[34:35], v[162:163]
	v_add_f32_e32 v51, v162, v163
	ds_read_b128 v[124:127], v67 offset:60416
	s_waitcnt lgkmcnt(6)
	v_pk_fma_f32 v[164:165], v[100:101], v[36:37], v[164:165]
	v_pk_fma_f32 v[164:165], v[102:103], v[34:35], v[164:165]
	v_add_f32_e32 v58, v164, v165
	ds_read_b128 v[128:131], v67 offset:64512
	s_waitcnt lgkmcnt(6)
	v_pk_fma_f32 v[168:169], v[104:105], v[36:37], v[168:169]
	v_pk_fma_f32 v[168:169], v[106:107], v[34:35], v[168:169]
	v_add_f32_e32 v60, v168, v169
	s_waitcnt lgkmcnt(5)
	v_pk_fma_f32 v[170:171], v[108:109], v[36:37], v[170:171]
	v_pk_fma_f32 v[170:171], v[110:111], v[34:35], v[170:171]
	v_add_f32_e32 v61, v170, v171
	s_waitcnt lgkmcnt(4)
	v_pk_fma_f32 v[172:173], v[112:113], v[36:37], v[172:173]
	v_pk_fma_f32 v[172:173], v[114:115], v[34:35], v[172:173]
	v_add_f32_e32 v68, v172, v173
	s_waitcnt lgkmcnt(3)
	v_pk_fma_f32 v[174:175], v[116:117], v[36:37], v[174:175]
	v_pk_fma_f32 v[174:175], v[118:119], v[34:35], v[174:175]
	v_add_f32_e32 v69, v174, v175
	s_waitcnt lgkmcnt(2)
	v_pk_fma_f32 v[176:177], v[120:121], v[36:37], v[176:177]
	v_pk_fma_f32 v[176:177], v[122:123], v[34:35], v[176:177]
	v_add_f32_e32 v70, v176, v177
	s_waitcnt lgkmcnt(1)
	v_pk_fma_f32 v[178:179], v[124:125], v[36:37], v[178:179]
	v_pk_fma_f32 v[178:179], v[126:127], v[34:35], v[178:179]
	v_add_f32_e32 v71, v178, v179
	s_waitcnt lgkmcnt(0)
	v_pk_fma_f32 v[180:181], v[128:129], v[36:37], v[180:181]
	v_pk_fma_f32 v[180:181], v[130:131], v[34:35], v[180:181]
	v_cndmask_b32_e32 v36, v39, v58, vcc
	v_add_f32_e32 v34, v180, v181
	ds_bpermute_b32 v36, v59, v36
	v_cndmask_b32_e32 v37, v40, v60, vcc
	ds_bpermute_b32 v37, v59, v37
	v_cndmask_b32_e32 v38, v41, v61, vcc
	ds_bpermute_b32 v38, v59, v38
	v_cndmask_b32_e32 v35, v58, v39, vcc
	v_cndmask_b32_e32 v39, v42, v68, vcc
	s_waitcnt lgkmcnt(2)
	v_add_f32_e32 v35, v35, v36
	v_cndmask_b32_e32 v36, v60, v40, vcc
	ds_bpermute_b32 v39, v59, v39
	v_cndmask_b32_e32 v40, v43, v69, vcc
	s_waitcnt lgkmcnt(2)
	v_add_f32_e32 v36, v36, v37
	v_cndmask_b32_e32 v37, v61, v41, vcc
	ds_bpermute_b32 v40, v59, v40
	v_cndmask_b32_e32 v41, v48, v70, vcc
	s_waitcnt lgkmcnt(2)
	v_add_f32_e32 v37, v37, v38
	v_cndmask_b32_e32 v38, v68, v42, vcc
	ds_bpermute_b32 v41, v59, v41
	v_cndmask_b32_e32 v42, v49, v71, vcc
	ds_bpermute_b32 v42, v59, v42
	s_waitcnt lgkmcnt(3)
	v_add_f32_e32 v38, v38, v39
	v_cndmask_b32_e32 v39, v69, v43, vcc
	s_waitcnt lgkmcnt(2)
	v_add_f32_e32 v39, v39, v40
	v_cndmask_b32_e32 v40, v70, v48, vcc
	s_waitcnt lgkmcnt(1)
	v_add_f32_e32 v40, v40, v41
	v_cndmask_b32_e32 v41, v71, v49, vcc
	s_waitcnt lgkmcnt(0)
	v_add_f32_e32 v41, v41, v42
	v_cndmask_b32_e32 v42, v34, v51, vcc
	v_cndmask_b32_e32 v34, v51, v34, vcc
	ds_bpermute_b32 v34, v59, v34
	s_waitcnt lgkmcnt(0)
	v_add_f32_e32 v34, v42, v34
	v_cndmask_b32_e64 v42, v39, v35, s[36:37]
	v_cndmask_b32_e64 v35, v35, v39, s[36:37]
	v_cndmask_b32_e64 v39, v40, v36, s[36:37]
	v_cndmask_b32_e64 v36, v36, v40, s[36:37]
	ds_bpermute_b32 v36, v62, v36
	ds_bpermute_b32 v35, v62, v35
	s_waitcnt lgkmcnt(1)
	v_add_f32_e32 v36, v39, v36
	v_cndmask_b32_e64 v39, v41, v37, s[36:37]
	v_cndmask_b32_e64 v37, v37, v41, s[36:37]
	ds_bpermute_b32 v37, v62, v37
	s_waitcnt lgkmcnt(1)
	v_add_f32_e32 v35, v42, v35
	s_waitcnt lgkmcnt(0)
	v_add_f32_e32 v37, v39, v37
	v_cndmask_b32_e64 v39, v34, v38, s[36:37]
	v_cndmask_b32_e64 v34, v38, v34, s[36:37]
	ds_bpermute_b32 v34, v62, v34
	v_cndmask_b32_e64 v38, v37, v35, s[38:39]
	v_cndmask_b32_e64 v35, v35, v37, s[38:39]
	ds_bpermute_b32 v35, v63, v35
	s_waitcnt lgkmcnt(1)
	v_add_f32_e32 v34, v39, v34
	v_cndmask_b32_e64 v37, v34, v36, s[38:39]
	v_cndmask_b32_e64 v34, v36, v34, s[38:39]
	ds_bpermute_b32 v34, v63, v34
	s_waitcnt lgkmcnt(1)
	v_add_f32_e32 v35, v38, v35
	s_waitcnt lgkmcnt(0)
	v_add_f32_e32 v34, v37, v34
	v_cndmask_b32_e64 v36, v34, v35, s[40:41]
	v_cndmask_b32_e64 v34, v35, v34, s[40:41]
	ds_bpermute_b32 v34, v64, v34
	s_waitcnt lgkmcnt(0)
	v_add_f32_e32 v34, v36, v34
	s_nop 1
	v_mov_b32_dpp v35, v34 quad_perm:[2,3,0,1] row_mask:0xf bank_mask:0xf
	s_waitcnt lgkmcnt(0)
	v_add_f32_e32 v34, v34, v35
	s_nop 1
	v_mov_b32_dpp v35, v34 quad_perm:[1,0,3,2] row_mask:0xf bank_mask:0xf
	s_and_saveexec_b64 s[0:1], s[42:43]
	s_cbranch_execz .LBB0_239
	v_lshl_add_u64 v[36:37], s[74:75], 0, v[52:53]
	s_waitcnt lgkmcnt(0)
	v_add_f32_e32 v34, v34, v35
	global_store_dword v[36:37], v34, off
	s_branch .LBB0_239

; #define LAS __attribute__((address_space(3)))
; __device__ __forceinline__ unsigned cvt_pk_bf16(float lo, float hi) { unsigned r; asm volatile("v_cvt_pk_bf16_f32 %0, %1, %2" : "=v"(r) : "v"(lo), "v"(hi)); return r; }
; __device__ void phase_norm_alow(const Params& P, int l, int half, LAS unsigned char* lds) {
;     ...
;         for (int i = 0; i < 4; ++i) { v[i] = nv[i]; ss += v[i][0] * v[i][0] + v[i][1] * v[i][1] + v[i][2] * v[i][2] + v[i][3] * v[i][3]; }
;         if (row + rstride < TH) {
; #pragma unroll
;             for (int i = 0; i < 4; ++i) nv[i] = *(const f32x4*)(xs + (size_t)(row + rstride) * DM + i * 256 + lane * 4);
;         }
;         ss = wave_sum(ss);
;         const float r = rsqrtf(ss * (1.0f / DM) + EPS);
;         float a[16];
; #pragma unroll
;         for (int c = 0; c < 16; ++c) a[c] = 0.f;
; #pragma unroll
;         for (int i = 0; i < 4; ++i) { f32x4 h = v[i] * r * gv[i];
;             u32x2 w; w.x = cvt_pk_bf16(h[0], h[1]); w.y = cvt_pk_bf16(h[2], h[3]);
;             *(u32x2*)(H + (size_t)row * DM + i * 256 + lane * 4) = w;
; #pragma unroll
;             for (int c = 0; c < 16; ++c) { const f32x4 wv = *(const LAS f32x4*)(WaT + c * 1024 + i * 256 + lane * 4); a[c] += h[0] * wv[0] + h[1] * wv[1] + h[2] * wv[2] + h[3] * wv[3]; } }
.LBB0_680:
	s_or_b64 exec, exec, s[30:31]
	v_mul_f32_e32 v51, v47, v47
	v_mul_f32_e32 v58, v43, v43
	v_fmac_f32_e32 v51, v46, v46
	v_fmac_f32_e32 v58, v42, v42
	v_fmac_f32_e32 v51, v48, v48
	v_fmac_f32_e32 v58, v44, v44
	v_fmac_f32_e32 v51, v49, v49
	v_fmac_f32_e32 v58, v45, v45
	v_add_f32_e32 v51, v51, v58
	v_mul_f32_e32 v58, v39, v39
	v_fmac_f32_e32 v58, v38, v38
	v_fmac_f32_e32 v58, v40, v40
	v_fmac_f32_e32 v58, v41, v41
	v_add_f32_e32 v51, v51, v58
	v_mul_f32_e32 v58, v35, v35
	v_fmac_f32_e32 v58, v34, v34
	v_fmac_f32_e32 v58, v36, v36
	v_fmac_f32_e32 v58, v37, v37
	v_add_f32_e32 v51, v51, v58
	v_mov_b32_e32 v58, v51
	s_nop 1
	v_permlane32_swap_b32_e32 v58, v51
	s_nop 1
	v_lshl_add_u64 v[68:69], s[74:75], 0, v[56:57]
	s_waitcnt lgkmcnt(0)
	v_add_f32_e32 v51, v51, v58
	v_mov_b32_e32 v58, v51
	s_nop 1
	v_permlane16_swap_b32_e32 v58, v51
	s_nop 1
	s_waitcnt lgkmcnt(0)
	v_add_f32_e32 v51, v51, v58
	s_nop 1
	v_mov_b32_dpp v58, v51 row_ror:8 row_mask:0xf bank_mask:0xf
	s_waitcnt lgkmcnt(0)
	v_add_f32_e32 v51, v51, v58
	s_nop 1
	v_mov_b32_dpp v58, v51 row_shl:4 row_mask:0xf bank_mask:0x5
	s_nop 1
	v_mov_b32_dpp v58, v51 row_shr:4 row_mask:0xf bank_mask:0xa
	s_waitcnt lgkmcnt(0)
	v_add_f32_e32 v51, v51, v58
	s_nop 1
	v_mov_b32_dpp v58, v51 quad_perm:[2,3,0,1] row_mask:0xf bank_mask:0xf
	s_waitcnt lgkmcnt(0)
	v_add_f32_e32 v51, v51, v58
	s_nop 1
	v_mov_b32_dpp v58, v51 quad_perm:[1,0,3,2] row_mask:0xf bank_mask:0xf
	s_waitcnt lgkmcnt(0)
	v_add_f32_e32 v51, v51, v58
	v_fmamk_f32 v51, v51, 0x3a800000, v1
	v_cmp_gt_f32_e64 s[0:1], s33, v51
	v_mul_f32_e32 v58, 0x4b800000, v51
	s_nop 0
	v_cndmask_b32_e64 v51, v51, v58, s[0:1]
	v_rsq_f32_e32 v51, v51
	s_nop 0
	v_mul_f32_e32 v58, 0x45800000, v51
	v_cndmask_b32_e64 v58, v51, v58, s[0:1]
	v_pk_mul_f32 v[46:47], v[46:47], v[58:59] op_sel_hi:[1,0]
	s_mov_b32 s0, 0x3a88000
	v_pk_mul_f32 v[48:49], v[48:49], v[58:59] op_sel_hi:[1,0]
	v_pk_mul_f32 v[60:61], v[14:15], v[46:47]
	v_add_co_u32_e64 v46, s[0:1], s0, v68
	v_pk_mul_f32 v[48:49], v[16:17], v[48:49]
	v_cvt_pk_bf16_f32 v70, v60, v61
	s_nop 0
	v_addc_co_u32_e64 v47, s[0:1], 0, v69, s[0:1]
	v_cvt_pk_bf16_f32 v71, v48, v49
	global_store_dwordx2 v[46:47], v[70:71], off
	ds_read_b128 v[100:103], v67
	ds_read_b128 v[104:107], v67 offset:4096
	ds_read_b128 v[108:111], v67 offset:8192
	ds_read_b128 v[112:115], v67 offset:12288
	ds_read_b128 v[116:119], v67 offset:16384
	ds_read_b128 v[120:123], v67 offset:20480
	ds_read_b128 v[124:127], v67 offset:24576
	s_waitcnt lgkmcnt(6)
	v_pk_mul_f32 v[148:149], v[100:101], v[60:61]
	v_pk_fma_f32 v[148:149], v[102:103], v[48:49], v[148:149]
	ds_read_b128 v[128:131], v67 offset:28672
	s_waitcnt lgkmcnt(6)
	v_pk_mul_f32 v[150:151], v[104:105], v[60:61]
	v_pk_fma_f32 v[150:151], v[106:107], v[48:49], v[150:151]
	ds_read_b128 v[100:103], v67 offset:32768
	s_waitcnt lgkmcnt(6)
	v_pk_mul_f32 v[152:153], v[108:109], v[60:61]
	v_pk_fma_f32 v[152:153], v[110:111], v[48:49], v[152:153]
	ds_read_b128 v[104:107], v67 offset:36864
	s_waitcnt lgkmcnt(6)
	v_pk_mul_f32 v[154:155], v[112:113], v[60:61]
	v_pk_fma_f32 v[154:155], v[114:115], v[48:49], v[154:155]
	ds_read_b128 v[108:111], v67 offset:40960
	s_waitcnt lgkmcnt(6)
	v_pk_mul_f32 v[156:157], v[116:117], v[60:61]
	v_pk_fma_f32 v[156:157], v[118:119], v[48:49], v[156:157]
	ds_read_b128 v[112:115], v67 offset:45056
	s_waitcnt lgkmcnt(6)
	v_pk_mul_f32 v[158:159], v[120:121], v[60:61]
	v_pk_fma_f32 v[158:159], v[122:123], v[48:49], v[158:159]
	ds_read_b128 v[116:119], v67 offset:49152
	s_waitcnt lgkmcnt(6)
	v_pk_mul_f32 v[160:161], v[124:125], v[60:61]
	v_pk_fma_f32 v[160:161], v[126:127], v[48:49], v[160:161]
	ds_read_b128 v[120:123], v67 offset:53248
	s_waitcnt lgkmcnt(6)
	v_pk_mul_f32 v[162:163], v[128:129], v[60:61]
	v_pk_fma_f32 v[162:163], v[130:131], v[48:49], v[162:163]
	ds_read_b128 v[124:127], v67 offset:57344
	s_waitcnt lgkmcnt(6)
	v_pk_mul_f32 v[164:165], v[100:101], v[60:61]
	v_pk_fma_f32 v[164:165], v[102:103], v[48:49], v[164:165]
	ds_read_b128 v[128:131], v67 offset:61440
	s_waitcnt lgkmcnt(6)
	v_pk_mul_f32 v[168:169], v[104:105], v[60:61]
	v_pk_fma_f32 v[168:169], v[106:107], v[48:49], v[168:169]
	ds_read_b128 v[100:103], v67 offset:1024
	s_waitcnt lgkmcnt(6)
	v_pk_mul_f32 v[170:171], v[108:109], v[60:61]
	v_pk_fma_f32 v[170:171], v[110:111], v[48:49], v[170:171]
	ds_read_b128 v[104:107], v67 offset:5120
	s_waitcnt lgkmcnt(6)
	v_pk_mul_f32 v[172:173], v[112:113], v[60:61]
	v_pk_fma_f32 v[172:173], v[114:115], v[48:49], v[172:173]
	ds_read_b128 v[108:111], v67 offset:9216
	s_waitcnt lgkmcnt(6)
	v_pk_mul_f32 v[174:175], v[116:117], v[60:61]
	v_pk_fma_f32 v[174:175], v[118:119], v[48:49], v[174:175]
	ds_read_b128 v[112:115], v67 offset:13312
	s_waitcnt lgkmcnt(6)
	v_pk_mul_f32 v[176:177], v[120:121], v[60:61]
	v_pk_fma_f32 v[176:177], v[122:123], v[48:49], v[176:177]
	ds_read_b128 v[116:119], v67 offset:17408
	s_waitcnt lgkmcnt(6)
	v_pk_mul_f32 v[178:179], v[124:125], v[60:61]
	v_pk_fma_f32 v[178:179], v[126:127], v[48:49], v[178:179]
	ds_read_b128 v[120:123], v67 offset:21504
	s_waitcnt lgkmcnt(6)
	v_pk_mul_f32 v[180:181], v[128:129], v[60:61]
	v_pk_fma_f32 v[180:181], v[130:131], v[48:49], v[180:181]
	v_pk_mul_f32 v[60:61], v[42:43], v[58:59] op_sel_hi:[1,0]
	v_pk_mul_f32 v[42:43], v[44:45], v[58:59] op_sel_hi:[1,0]
	v_pk_mul_f32 v[44:45], v[10:11], v[60:61]
	v_pk_mul_f32 v[42:43], v[12:13], v[42:43]
	v_cvt_pk_bf16_f32 v60, v44, v45
	s_nop 0
	v_cvt_pk_bf16_f32 v61, v42, v43
	ds_read_b128 v[124:127], v67 offset:25600
	global_store_dwordx2 v[46:47], v[60:61], off offset:512
	s_waitcnt lgkmcnt(6)
; #define LAS __attribute__((address_space(3)))
; __device__ __forceinline__ unsigned cvt_pk_bf16(float lo, float hi) { unsigned r; asm volatile("v_cvt_pk_bf16_f32 %0, %1, %2" : "=v"(r) : "v"(lo), "v"(hi)); return r; }
; __device__ void phase_norm_alow(const Params& P, int l, int half, LAS unsigned char* lds) {
;     ...
;         for (int i = 0; i < 4; ++i) { f32x4 h = v[i] * r * gv[i];
;             u32x2 w; w.x = cvt_pk_bf16(h[0], h[1]); w.y = cvt_pk_bf16(h[2], h[3]);
;             *(u32x2*)(H + (size_t)row * DM + i * 256 + lane * 4) = w;
; #pragma unroll
;             for (int c = 0; c < 16; ++c) { const f32x4 wv = *(const LAS f32x4*)(WaT + c * 1024 + i * 256 + lane * 4); a[c] += h[0] * wv[0] + h[1] * wv[1] + h[2] * wv[2] + h[3] * wv[3]; } }
	v_pk_fma_f32 v[148:149], v[100:101], v[44:45], v[148:149]
	v_pk_fma_f32 v[148:149], v[102:103], v[42:43], v[148:149]
	ds_read_b128 v[128:131], v67 offset:29696
	s_waitcnt lgkmcnt(6)
	v_pk_fma_f32 v[150:151], v[104:105], v[44:45], v[150:151]
	v_pk_fma_f32 v[150:151], v[106:107], v[42:43], v[150:151]
	ds_read_b128 v[100:103], v67 offset:33792
	s_waitcnt lgkmcnt(6)
	v_pk_fma_f32 v[152:153], v[108:109], v[44:45], v[152:153]
	v_pk_fma_f32 v[152:153], v[110:111], v[42:43], v[152:153]
	ds_read_b128 v[104:107], v67 offset:37888
	s_waitcnt lgkmcnt(6)
	v_pk_fma_f32 v[154:155], v[112:113], v[44:45], v[154:155]
	v_pk_fma_f32 v[154:155], v[114:115], v[42:43], v[154:155]
	ds_read_b128 v[108:111], v67 offset:41984
	s_waitcnt lgkmcnt(6)
	v_pk_fma_f32 v[156:157], v[116:117], v[44:45], v[156:157]
	v_pk_fma_f32 v[156:157], v[118:119], v[42:43], v[156:157]
	ds_read_b128 v[112:115], v67 offset:46080
	s_waitcnt lgkmcnt(6)
	v_pk_fma_f32 v[158:159], v[120:121], v[44:45], v[158:159]
	v_pk_fma_f32 v[158:159], v[122:123], v[42:43], v[158:159]
	ds_read_b128 v[116:119], v67 offset:50176
	s_waitcnt lgkmcnt(6)
	v_pk_fma_f32 v[160:161], v[124:125], v[44:45], v[160:161]
	v_pk_fma_f32 v[160:161], v[126:127], v[42:43], v[160:161]
	ds_read_b128 v[120:123], v67 offset:54272
	s_waitcnt lgkmcnt(6)
	v_pk_fma_f32 v[162:163], v[128:129], v[44:45], v[162:163]
	v_pk_fma_f32 v[162:163], v[130:131], v[42:43], v[162:163]
	ds_read_b128 v[124:127], v67 offset:58368
	s_waitcnt lgkmcnt(6)
	v_pk_fma_f32 v[164:165], v[100:101], v[44:45], v[164:165]
	v_pk_fma_f32 v[164:165], v[102:103], v[42:43], v[164:165]
	ds_read_b128 v[128:131], v67 offset:62464
	s_waitcnt lgkmcnt(6)
	v_pk_fma_f32 v[168:169], v[104:105], v[44:45], v[168:169]
	v_pk_fma_f32 v[168:169], v[106:107], v[42:43], v[168:169]
	ds_read_b128 v[100:103], v67 offset:2048
	s_waitcnt lgkmcnt(6)
	v_pk_fma_f32 v[170:171], v[108:109], v[44:45], v[170:171]
	v_pk_fma_f32 v[170:171], v[110:111], v[42:43], v[170:171]
	ds_read_b128 v[104:107], v67 offset:6144
	s_waitcnt lgkmcnt(6)
	v_pk_fma_f32 v[172:173], v[112:113], v[44:45], v[172:173]
	v_pk_fma_f32 v[172:173], v[114:115], v[42:43], v[172:173]
	ds_read_b128 v[108:111], v67 offset:10240
	s_waitcnt lgkmcnt(6)
	v_pk_fma_f32 v[174:175], v[116:117], v[44:45], v[174:175]
	v_pk_fma_f32 v[174:175], v[118:119], v[42:43], v[174:175]
	ds_read_b128 v[112:115], v67 offset:14336
	s_waitcnt lgkmcnt(6)
	v_pk_fma_f32 v[176:177], v[120:121], v[44:45], v[176:177]
	v_pk_fma_f32 v[176:177], v[122:123], v[42:43], v[176:177]
	ds_read_b128 v[116:119], v67 offset:18432
	s_waitcnt lgkmcnt(6)
	v_pk_fma_f32 v[178:179], v[124:125], v[44:45], v[178:179]
	v_pk_fma_f32 v[178:179], v[126:127], v[42:43], v[178:179]
	ds_read_b128 v[120:123], v67 offset:22528
	s_waitcnt lgkmcnt(6)
	v_pk_fma_f32 v[180:181], v[128:129], v[44:45], v[180:181]
	v_pk_fma_f32 v[180:181], v[130:131], v[42:43], v[180:181]
	v_pk_mul_f32 v[42:43], v[38:39], v[58:59] op_sel_hi:[1,0]
	v_pk_mul_f32 v[38:39], v[40:41], v[58:59] op_sel_hi:[1,0]
	v_pk_mul_f32 v[40:41], v[6:7], v[42:43]
	v_pk_mul_f32 v[38:39], v[8:9], v[38:39]
	v_cvt_pk_bf16_f32 v42, v40, v41
	v_cvt_pk_bf16_f32 v43, v38, v39
	global_store_dwordx2 v[46:47], v[42:43], off offset:1024
	ds_read_b128 v[124:127], v67 offset:26624
	ds_read_b128 v[128:131], v67 offset:30720
	s_waitcnt lgkmcnt(7)
	v_pk_fma_f32 v[148:149], v[100:101], v[40:41], v[148:149]
	v_pk_fma_f32 v[148:149], v[102:103], v[38:39], v[148:149]
	s_waitcnt lgkmcnt(6)
	v_pk_fma_f32 v[150:151], v[104:105], v[40:41], v[150:151]
	v_pk_fma_f32 v[150:151], v[106:107], v[38:39], v[150:151]
	ds_read_b128 v[100:103], v67 offset:34816
	s_waitcnt lgkmcnt(6)
	v_pk_fma_f32 v[152:153], v[108:109], v[40:41], v[152:153]
	v_pk_fma_f32 v[152:153], v[110:111], v[38:39], v[152:153]
	ds_read_b128 v[104:107], v67 offset:38912
	s_waitcnt lgkmcnt(6)
	v_pk_fma_f32 v[154:155], v[112:113], v[40:41], v[154:155]
	v_pk_fma_f32 v[154:155], v[114:115], v[38:39], v[154:155]
	ds_read_b128 v[108:111], v67 offset:43008
	s_waitcnt lgkmcnt(6)
	v_pk_fma_f32 v[156:157], v[116:117], v[40:41], v[156:157]
	v_pk_fma_f32 v[156:157], v[118:119], v[38:39], v[156:157]
	ds_read_b128 v[112:115], v67 offset:47104
	s_waitcnt lgkmcnt(6)
	v_pk_fma_f32 v[158:159], v[120:121], v[40:41], v[158:159]
	v_pk_fma_f32 v[158:159], v[122:123], v[38:39], v[158:159]
	ds_read_b128 v[116:119], v67 offset:51200
	s_waitcnt lgkmcnt(6)
	v_pk_fma_f32 v[160:161], v[124:125], v[40:41], v[160:161]
	v_pk_fma_f32 v[160:161], v[126:127], v[38:39], v[160:161]
	ds_read_b128 v[120:123], v67 offset:55296
	s_waitcnt lgkmcnt(6)
	v_pk_fma_f32 v[162:163], v[128:129], v[40:41], v[162:163]
	v_pk_fma_f32 v[162:163], v[130:131], v[38:39], v[162:163]
	ds_read_b128 v[124:127], v67 offset:59392
	s_waitcnt lgkmcnt(6)
	v_pk_fma_f32 v[164:165], v[100:101], v[40:41], v[164:165]
	v_pk_fma_f32 v[164:165], v[102:103], v[38:39], v[164:165]
	ds_read_b128 v[128:131], v67 offset:63488
	s_waitcnt lgkmcnt(6)
	v_pk_fma_f32 v[168:169], v[104:105], v[40:41], v[168:169]
	v_pk_fma_f32 v[168:169], v[106:107], v[38:39], v[168:169]
	ds_read_b128 v[100:103], v67 offset:3072
	s_waitcnt lgkmcnt(6)
	v_pk_fma_f32 v[170:171], v[108:109], v[40:41], v[170:171]
	v_pk_fma_f32 v[170:171], v[110:111], v[38:39], v[170:171]
	ds_read_b128 v[104:107], v67 offset:7168
	s_waitcnt lgkmcnt(6)
	v_pk_fma_f32 v[172:173], v[112:113], v[40:41], v[172:173]
	v_pk_fma_f32 v[172:173], v[114:115], v[38:39], v[172:173]
	ds_read_b128 v[108:111], v67 offset:11264
	s_waitcnt lgkmcnt(6)
	v_pk_fma_f32 v[174:175], v[116:117], v[40:41], v[174:175]
	v_pk_fma_f32 v[174:175], v[118:119], v[38:39], v[174:175]
	ds_read_b128 v[112:115], v67 offset:15360
	s_waitcnt lgkmcnt(6)
; #define LAS __attribute__((address_space(3)))
; __device__ __forceinline__ unsigned cvt_pk_bf16(float lo, float hi) { unsigned r; asm volatile("v_cvt_pk_bf16_f32 %0, %1, %2" : "=v"(r) : "v"(lo), "v"(hi)); return r; }
; __device__ void phase_norm_alow(const Params& P, int l, int half, LAS unsigned char* lds) {
;     ...
;         for (int i = 0; i < 4; ++i) { f32x4 h = v[i] * r * gv[i];
;             u32x2 w; w.x = cvt_pk_bf16(h[0], h[1]); w.y = cvt_pk_bf16(h[2], h[3]);
;             *(u32x2*)(H + (size_t)row * DM + i * 256 + lane * 4) = w;
; #pragma unroll
;             for (int c = 0; c < 16; ++c) { const f32x4 wv = *(const LAS f32x4*)(WaT + c * 1024 + i * 256 + lane * 4); a[c] += h[0] * wv[0] + h[1] * wv[1] + h[2] * wv[2] + h[3] * wv[3]; } }
;         float b8[8], b4[4], b2[2], b1;
;         { const bool up = (lane & 32) != 0;
; #pragma unroll
;           for (int c = 0; c < 8; ++c) { const float keep = up ? a[c + 8] : a[c], send = up ? a[c] : a[c + 8]; b8[c] = keep + __shfl_xor(send, 32); } }
;         { const bool up = (lane & 16) != 0;
; #pragma unroll
;           for (int c = 0; c < 4; ++c) { const float keep = up ? b8[c + 4] : b8[c], send = up ? b8[c] : b8[c + 4]; b4[c] = keep + __shfl_xor(send, 16); } }
;         { const bool up = (lane & 8) != 0;
; #pragma unroll
;           for (int c = 0; c < 2; ++c) { const float keep = up ? b4[c + 2] : b4[c], send = up ? b4[c] : b4[c + 2]; b2[c] = keep + __shfl_xor(send, 8); } }
;         { const bool up = (lane & 4) != 0; const float keep = up ? b2[1] : b2[0], send = up ? b2[0] : b2[1]; b1 = keep + __shfl_xor(send, 4); }
;         b1 += __shfl_xor(b1, 2); b1 += __shfl_xor(b1, 1);
;         if ((lane & 3) == 0) { const int co = ((lane >> 5) & 1) * 8 + ((lane >> 4) & 1) * 4 + ((lane >> 3) & 1) * 2 + ((lane >> 2) & 1); AL[(size_t)row * 16 + co] = b1; }
	v_pk_fma_f32 v[176:177], v[120:121], v[40:41], v[176:177]
	v_pk_fma_f32 v[176:177], v[122:123], v[38:39], v[176:177]
	ds_read_b128 v[116:119], v67 offset:19456
	s_waitcnt lgkmcnt(6)
	v_pk_fma_f32 v[178:179], v[124:125], v[40:41], v[178:179]
	v_pk_fma_f32 v[178:179], v[126:127], v[38:39], v[178:179]
	ds_read_b128 v[120:123], v67 offset:23552
	s_waitcnt lgkmcnt(6)
	v_pk_fma_f32 v[180:181], v[128:129], v[40:41], v[180:181]
	v_pk_fma_f32 v[180:181], v[130:131], v[38:39], v[180:181]
	v_pk_mul_f32 v[40:41], v[34:35], v[58:59] op_sel_hi:[1,0]
	v_pk_mul_f32 v[34:35], v[36:37], v[58:59] op_sel_hi:[1,0]
	v_pk_mul_f32 v[36:37], v[2:3], v[40:41]
	v_pk_mul_f32 v[34:35], v[4:5], v[34:35]
	v_cvt_pk_bf16_f32 v40, v36, v37
	s_nop 0
	v_cvt_pk_bf16_f32 v41, v34, v35
	ds_read_b128 v[124:127], v67 offset:27648
	global_store_dwordx2 v[46:47], v[40:41], off offset:1536
	s_waitcnt lgkmcnt(6)
	v_pk_fma_f32 v[148:149], v[100:101], v[36:37], v[148:149]
	v_pk_fma_f32 v[148:149], v[102:103], v[34:35], v[148:149]
	ds_read_b128 v[128:131], v67 offset:31744
	v_add_f32_e32 v39, v148, v149
	s_waitcnt lgkmcnt(6)
	v_pk_fma_f32 v[150:151], v[104:105], v[36:37], v[150:151]
	v_pk_fma_f32 v[150:151], v[106:107], v[34:35], v[150:151]
	ds_read_b128 v[100:103], v67 offset:35840
	v_add_f32_e32 v40, v150, v151
	s_waitcnt lgkmcnt(6)
	v_pk_fma_f32 v[152:153], v[108:109], v[36:37], v[152:153]
	v_pk_fma_f32 v[152:153], v[110:111], v[34:35], v[152:153]
	ds_read_b128 v[104:107], v67 offset:39936
	v_add_f32_e32 v41, v152, v153
	s_waitcnt lgkmcnt(6)
	v_pk_fma_f32 v[154:155], v[112:113], v[36:37], v[154:155]
	v_pk_fma_f32 v[154:155], v[114:115], v[34:35], v[154:155]
	v_add_f32_e32 v42, v154, v155
	ds_read_b128 v[108:111], v67 offset:44032
	s_waitcnt lgkmcnt(6)
	v_pk_fma_f32 v[156:157], v[116:117], v[36:37], v[156:157]
	v_pk_fma_f32 v[156:157], v[118:119], v[34:35], v[156:157]
	ds_read_b128 v[112:115], v67 offset:48128
	v_add_f32_e32 v43, v156, v157
	s_waitcnt lgkmcnt(6)
	v_pk_fma_f32 v[158:159], v[120:121], v[36:37], v[158:159]
	v_pk_fma_f32 v[158:159], v[122:123], v[34:35], v[158:159]
	v_add_f32_e32 v48, v158, v159
	ds_read_b128 v[116:119], v67 offset:52224
	s_waitcnt lgkmcnt(6)
	v_pk_fma_f32 v[160:161], v[124:125], v[36:37], v[160:161]
	v_pk_fma_f32 v[160:161], v[126:127], v[34:35], v[160:161]
	v_add_f32_e32 v49, v160, v161
	ds_read_b128 v[120:123], v67 offset:56320
	s_waitcnt lgkmcnt(6)
	v_pk_fma_f32 v[162:163], v[128:129], v[36:37], v[162:163]
	v_pk_fma_f32 v[162:163], v[130:131], v[34:35], v[162:163]
	v_add_f32_e32 v51, v162, v163
	ds_read_b128 v[124:127], v67 offset:60416
	s_waitcnt lgkmcnt(6)
	v_pk_fma_f32 v[164:165], v[100:101], v[36:37], v[164:165]
	v_pk_fma_f32 v[164:165], v[102:103], v[34:35], v[164:165]
	v_add_f32_e32 v58, v164, v165
	ds_read_b128 v[128:131], v67 offset:64512
	s_waitcnt lgkmcnt(6)
	v_pk_fma_f32 v[168:169], v[104:105], v[36:37], v[168:169]
	v_pk_fma_f32 v[168:169], v[106:107], v[34:35], v[168:169]
	v_add_f32_e32 v60, v168, v169
	s_waitcnt lgkmcnt(5)
	v_pk_fma_f32 v[170:171], v[108:109], v[36:37], v[170:171]
	v_pk_fma_f32 v[170:171], v[110:111], v[34:35], v[170:171]
	v_add_f32_e32 v61, v170, v171
	s_waitcnt lgkmcnt(4)
	v_pk_fma_f32 v[172:173], v[112:113], v[36:37], v[172:173]
	v_pk_fma_f32 v[172:173], v[114:115], v[34:35], v[172:173]
	v_add_f32_e32 v68, v172, v173
	s_waitcnt lgkmcnt(3)
	v_pk_fma_f32 v[174:175], v[116:117], v[36:37], v[174:175]
	v_pk_fma_f32 v[174:175], v[118:119], v[34:35], v[174:175]
	v_add_f32_e32 v69, v174, v175
	s_waitcnt lgkmcnt(2)
	v_pk_fma_f32 v[176:177], v[120:121], v[36:37], v[176:177]
	v_pk_fma_f32 v[176:177], v[122:123], v[34:35], v[176:177]
	v_add_f32_e32 v70, v176, v177
	s_waitcnt lgkmcnt(1)
	v_pk_fma_f32 v[178:179], v[124:125], v[36:37], v[178:179]
	v_pk_fma_f32 v[178:179], v[126:127], v[34:35], v[178:179]
	v_add_f32_e32 v71, v178, v179
	s_waitcnt lgkmcnt(0)
	v_pk_fma_f32 v[180:181], v[128:129], v[36:37], v[180:181]
	v_pk_fma_f32 v[180:181], v[130:131], v[34:35], v[180:181]
	v_cndmask_b32_e32 v36, v39, v58, vcc
	v_add_f32_e32 v34, v180, v181
	ds_bpermute_b32 v36, v59, v36
	v_cndmask_b32_e32 v37, v40, v60, vcc
	ds_bpermute_b32 v37, v59, v37
	v_cndmask_b32_e32 v38, v41, v61, vcc
	ds_bpermute_b32 v38, v59, v38
	v_cndmask_b32_e32 v35, v58, v39, vcc
	v_cndmask_b32_e32 v39, v42, v68, vcc
	s_waitcnt lgkmcnt(2)
	v_add_f32_e32 v35, v35, v36
	v_cndmask_b32_e32 v36, v60, v40, vcc
	ds_bpermute_b32 v39, v59, v39
	v_cndmask_b32_e32 v40, v43, v69, vcc
	s_waitcnt lgkmcnt(2)
	v_add_f32_e32 v36, v36, v37
	v_cndmask_b32_e32 v37, v61, v41, vcc
	ds_bpermute_b32 v40, v59, v40
	v_cndmask_b32_e32 v41, v48, v70, vcc
	s_waitcnt lgkmcnt(2)
	v_add_f32_e32 v37, v37, v38
	v_cndmask_b32_e32 v38, v68, v42, vcc
	ds_bpermute_b32 v41, v59, v41
	v_cndmask_b32_e32 v42, v49, v71, vcc
	ds_bpermute_b32 v42, v59, v42
	s_waitcnt lgkmcnt(3)
	v_add_f32_e32 v38, v38, v39
	v_cndmask_b32_e32 v39, v69, v43, vcc
	s_waitcnt lgkmcnt(2)
	v_add_f32_e32 v39, v39, v40
	v_cndmask_b32_e32 v40, v70, v48, vcc
	s_waitcnt lgkmcnt(1)
	v_add_f32_e32 v40, v40, v41
	v_cndmask_b32_e32 v41, v71, v49, vcc
	s_waitcnt lgkmcnt(0)
	v_add_f32_e32 v41, v41, v42
	v_cndmask_b32_e32 v42, v34, v51, vcc
	v_cndmask_b32_e32 v34, v51, v34, vcc
	ds_bpermute_b32 v34, v59, v34
	s_waitcnt lgkmcnt(0)
	v_add_f32_e32 v34, v42, v34
	v_cndmask_b32_e64 v42, v39, v35, s[36:37]
	v_cndmask_b32_e64 v35, v35, v39, s[36:37]
	v_cndmask_b32_e64 v39, v40, v36, s[36:37]
	v_cndmask_b32_e64 v36, v36, v40, s[36:37]
	ds_bpermute_b32 v36, v62, v36
	ds_bpermute_b32 v35, v62, v35
	s_waitcnt lgkmcnt(1)
	v_add_f32_e32 v36, v39, v36
	v_cndmask_b32_e64 v39, v41, v37, s[36:37]
	v_cndmask_b32_e64 v37, v37, v41, s[36:37]
	ds_bpermute_b32 v37, v62, v37
	s_waitcnt lgkmcnt(1)
	v_add_f32_e32 v35, v42, v35
	s_waitcnt lgkmcnt(0)
	v_add_f32_e32 v37, v39, v37
	v_cndmask_b32_e64 v39, v34, v38, s[36:37]
	v_cndmask_b32_e64 v34, v38, v34, s[36:37]
	ds_bpermute_b32 v34, v62, v34
	v_cndmask_b32_e64 v38, v37, v35, s[38:39]
	v_cndmask_b32_e64 v35, v35, v37, s[38:39]
	ds_bpermute_b32 v35, v63, v35
	s_waitcnt lgkmcnt(1)
	v_add_f32_e32 v34, v39, v34
	v_cndmask_b32_e64 v37, v34, v36, s[38:39]
	v_cndmask_b32_e64 v34, v36, v34, s[38:39]
	ds_bpermute_b32 v34, v63, v34
	s_waitcnt lgkmcnt(1)
	v_add_f32_e32 v35, v38, v35
	s_waitcnt lgkmcnt(0)
	v_add_f32_e32 v34, v37, v34
	v_cndmask_b32_e64 v36, v34, v35, s[40:41]
	v_cndmask_b32_e64 v34, v35, v34, s[40:41]
	ds_bpermute_b32 v34, v64, v34
	s_waitcnt lgkmcnt(0)
	v_add_f32_e32 v34, v36, v34
	s_nop 1
	v_mov_b32_dpp v35, v34 quad_perm:[2,3,0,1] row_mask:0xf bank_mask:0xf
	s_waitcnt lgkmcnt(0)
	v_add_f32_e32 v34, v34, v35
	s_nop 1
	v_mov_b32_dpp v35, v34 quad_perm:[1,0,3,2] row_mask:0xf bank_mask:0xf
	s_and_saveexec_b64 s[0:1], s[42:43]
	s_cbranch_execz .LBB0_677
	v_lshl_add_u64 v[36:37], s[74:75], 0, v[54:55]
	s_waitcnt lgkmcnt(0)
	v_add_f32_e32 v34, v34, v35
	global_store_dword v[36:37], v34, off
	s_branch .LBB0_677

; #define LAS __attribute__((address_space(3)))
; __device__ __forceinline__ unsigned cvt_pk_bf16(float lo, float hi) { unsigned r; asm volatile("v_cvt_pk_bf16_f32 %0, %1, %2" : "=v"(r) : "v"(lo), "v"(hi)); return r; }
; __device__ void phase_norm_alow(const Params& P, int l, int half, LAS unsigned char* lds) {
;     ...
;         for (int i = 0; i < 4; ++i) { v[i] = nv[i]; ss += v[i][0] * v[i][0] + v[i][1] * v[i][1] + v[i][2] * v[i][2] + v[i][3] * v[i][3]; }
;         if (row + rstride < TH) {
; #pragma unroll
;             for (int i = 0; i < 4; ++i) nv[i] = *(const f32x4*)(xs + (size_t)(row + rstride) * DM + i * 256 + lane * 4);
;         }
;         ss = wave_sum(ss);
;         const float r = rsqrtf(ss * (1.0f / DM) + EPS);
;         float a[16];
; #pragma unroll
;         for (int c = 0; c < 16; ++c) a[c] = 0.f;
; #pragma unroll
;         for (int i = 0; i < 4; ++i) { f32x4 h = v[i] * r * gv[i];
;             u32x2 w; w.x = cvt_pk_bf16(h[0], h[1]); w.y = cvt_pk_bf16(h[2], h[3]);
;             *(u32x2*)(H + (size_t)row * DM + i * 256 + lane * 4) = w;
; #pragma unroll
;             for (int c = 0; c < 16; ++c) { const f32x4 wv = *(const LAS f32x4*)(WaT + c * 1024 + i * 256 + lane * 4); a[c] += h[0] * wv[0] + h[1] * wv[1] + h[2] * wv[2] + h[3] * wv[3]; } }
.LBB0_755:
	s_or_b64 exec, exec, s[46:47]
	v_mul_f32_e32 v51, v47, v47
	v_mul_f32_e32 v58, v43, v43
	v_fmac_f32_e32 v51, v46, v46
	v_fmac_f32_e32 v58, v42, v42
	v_fmac_f32_e32 v51, v48, v48
	v_fmac_f32_e32 v58, v44, v44
	v_fmac_f32_e32 v51, v49, v49
	v_fmac_f32_e32 v58, v45, v45
	v_add_f32_e32 v51, v51, v58
	v_mul_f32_e32 v58, v39, v39
	v_fmac_f32_e32 v58, v38, v38
	v_fmac_f32_e32 v58, v40, v40
	v_fmac_f32_e32 v58, v41, v41
	v_add_f32_e32 v51, v51, v58
	v_mul_f32_e32 v58, v35, v35
	v_fmac_f32_e32 v58, v34, v34
	v_fmac_f32_e32 v58, v36, v36
	v_fmac_f32_e32 v58, v37, v37
	v_add_f32_e32 v51, v51, v58
	v_mov_b32_e32 v58, v51
	s_nop 1
	v_permlane32_swap_b32_e32 v58, v51
	s_nop 1
	s_mov_b32 s2, 0x3a88000
	s_waitcnt lgkmcnt(0)
	v_add_f32_e32 v51, v51, v58
	v_mov_b32_e32 v58, v51
	s_nop 1
	v_permlane16_swap_b32_e32 v58, v51
	s_nop 1
	s_waitcnt lgkmcnt(0)
	v_add_f32_e32 v51, v51, v58
	s_nop 1
	v_mov_b32_dpp v58, v51 row_ror:8 row_mask:0xf bank_mask:0xf
	s_waitcnt lgkmcnt(0)
	v_add_f32_e32 v51, v51, v58
	s_nop 1
	v_mov_b32_dpp v58, v51 row_shl:4 row_mask:0xf bank_mask:0x5
	s_nop 1
	v_mov_b32_dpp v58, v51 row_shr:4 row_mask:0xf bank_mask:0xa
	s_waitcnt lgkmcnt(0)
	v_add_f32_e32 v51, v51, v58
	s_nop 1
	v_mov_b32_dpp v58, v51 quad_perm:[2,3,0,1] row_mask:0xf bank_mask:0xf
	s_waitcnt lgkmcnt(0)
	v_add_f32_e32 v51, v51, v58
	s_nop 1
	v_mov_b32_dpp v60, v51 quad_perm:[1,0,3,2] row_mask:0xf bank_mask:0xf
	v_lshl_add_u64 v[58:59], s[74:75], 0, v[52:53]
	v_add_co_u32_e64 v58, s[46:47], s2, v58
	s_waitcnt lgkmcnt(0)
	v_add_f32_e32 v51, v51, v60
	v_fmamk_f32 v51, v51, 0x3a800000, v1
	v_mul_f32_e32 v60, 0x4b800000, v51
	v_cmp_gt_f32_e64 s[0:1], s33, v51
	v_addc_co_u32_e64 v59, s[46:47], 0, v59, s[46:47]
	s_nop 0
	v_cndmask_b32_e64 v51, v51, v60, s[0:1]
	v_rsq_f32_e32 v51, v51
	s_nop 0
	v_mul_f32_e32 v60, 0x45800000, v51
	v_cndmask_b32_e64 v60, v51, v60, s[0:1]
	v_pk_mul_f32 v[46:47], v[46:47], v[60:61] op_sel_hi:[1,0]
	v_pk_mul_f32 v[48:49], v[48:49], v[60:61] op_sel_hi:[1,0]
	s_waitcnt vmcnt(0)
	v_pk_mul_f32 v[82:83], v[14:15], v[46:47]
	v_pk_mul_f32 v[80:81], v[16:17], v[48:49]
	v_cvt_pk_bf16_f32 v84, v82, v83
	v_pk_mul_f32 v[42:43], v[42:43], v[60:61] op_sel_hi:[1,0]
	v_cvt_pk_bf16_f32 v85, v80, v81
	ds_read_b128 v[100:103], v61
	ds_read_b128 v[104:107], v61 offset:4096
	ds_read_b128 v[108:111], v61 offset:8192
	ds_read_b128 v[112:115], v61 offset:12288
	ds_read_b128 v[116:119], v61 offset:16384
	ds_read_b128 v[120:123], v61 offset:20480
	ds_read_b128 v[124:127], v61 offset:24576
	ds_read_b128 v[128:131], v61 offset:28672
	ds_read_b128 v[132:135], v61 offset:32768
	ds_read_b128 v[136:139], v61 offset:36864
	global_store_dwordx2 v[58:59], v[84:85], off
	s_waitcnt lgkmcnt(9)
	v_pk_mul_f32 v[148:149], v[100:101], v[82:83]
	s_waitcnt lgkmcnt(7)
	v_pk_mul_f32 v[150:151], v[108:109], v[82:83]
	v_pk_mul_f32 v[152:153], v[104:105], v[82:83]
	v_pk_fma_f32 v[148:149], v[102:103], v[80:81], v[148:149]
	v_pk_fma_f32 v[150:151], v[110:111], v[80:81], v[150:151]
	s_waitcnt lgkmcnt(6)
	v_pk_mul_f32 v[154:155], v[112:113], v[82:83]
	ds_read_b128 v[100:103], v61 offset:40960
	v_pk_fma_f32 v[154:155], v[114:115], v[80:81], v[154:155]
	v_pk_fma_f32 v[152:153], v[106:107], v[80:81], v[152:153]
	ds_read_b128 v[104:107], v61 offset:45056
	s_waitcnt lgkmcnt(7)
	v_pk_mul_f32 v[156:157], v[116:117], v[82:83]
	v_pk_fma_f32 v[156:157], v[118:119], v[80:81], v[156:157]
	s_waitcnt lgkmcnt(6)
	v_pk_mul_f32 v[158:159], v[120:121], v[82:83]
	ds_read_b128 v[108:111], v61 offset:49152
	v_pk_fma_f32 v[158:159], v[122:123], v[80:81], v[158:159]
	ds_read_b128 v[112:115], v61 offset:53248
	s_waitcnt lgkmcnt(7)
	v_pk_mul_f32 v[160:161], v[124:125], v[82:83]
	v_pk_fma_f32 v[160:161], v[126:127], v[80:81], v[160:161]
	s_waitcnt lgkmcnt(6)
	v_pk_mul_f32 v[162:163], v[128:129], v[82:83]
	ds_read_b128 v[116:119], v61 offset:57344
	v_pk_fma_f32 v[162:163], v[130:131], v[80:81], v[162:163]
	ds_read_b128 v[120:123], v61 offset:61440
	s_waitcnt lgkmcnt(7)
	v_pk_mul_f32 v[164:165], v[132:133], v[82:83]
	v_pk_fma_f32 v[164:165], v[134:135], v[80:81], v[164:165]
	s_waitcnt lgkmcnt(6)
	v_pk_mul_f32 v[168:169], v[136:137], v[82:83]
	ds_read_b128 v[124:127], v61 offset:1024
	v_pk_fma_f32 v[168:169], v[138:139], v[80:81], v[168:169]
	ds_read_b128 v[128:131], v61 offset:5120
	s_waitcnt lgkmcnt(7)
	v_pk_mul_f32 v[170:171], v[100:101], v[82:83]
	v_pk_fma_f32 v[170:171], v[102:103], v[80:81], v[170:171]
	s_waitcnt lgkmcnt(6)
	v_pk_mul_f32 v[172:173], v[104:105], v[82:83]
	ds_read_b128 v[132:135], v61 offset:9216
	v_pk_fma_f32 v[172:173], v[106:107], v[80:81], v[172:173]
	ds_read_b128 v[136:139], v61 offset:13312
	s_waitcnt lgkmcnt(7)
	v_pk_mul_f32 v[174:175], v[108:109], v[82:83]
	v_pk_fma_f32 v[174:175], v[110:111], v[80:81], v[174:175]
	s_waitcnt lgkmcnt(6)
	v_pk_mul_f32 v[176:177], v[112:113], v[82:83]
	ds_read_b128 v[100:103], v61 offset:17408
	v_pk_fma_f32 v[176:177], v[114:115], v[80:81], v[176:177]
	ds_read_b128 v[104:107], v61 offset:21504
	s_waitcnt lgkmcnt(7)
	v_pk_mul_f32 v[178:179], v[116:117], v[82:83]
	v_pk_fma_f32 v[178:179], v[118:119], v[80:81], v[178:179]
	s_waitcnt lgkmcnt(6)
	v_pk_mul_f32 v[180:181], v[120:121], v[82:83]
	v_pk_mul_f32 v[44:45], v[44:45], v[60:61] op_sel_hi:[1,0]
	v_pk_mul_f32 v[68:69], v[12:13], v[44:45]
	v_pk_mul_f32 v[72:73], v[10:11], v[42:43]
	v_pk_fma_f32 v[180:181], v[122:123], v[80:81], v[180:181]
	v_cvt_pk_bf16_f32 v46, v72, v73
	v_cvt_pk_bf16_f32 v47, v68, v69
	ds_read_b128 v[108:111], v61 offset:25600
	global_store_dwordx2 v[58:59], v[46:47], off offset:512
	ds_read_b128 v[112:115], v61 offset:29696
	s_waitcnt lgkmcnt(7)
; #define LAS __attribute__((address_space(3)))
; __device__ __forceinline__ unsigned cvt_pk_bf16(float lo, float hi) { unsigned r; asm volatile("v_cvt_pk_bf16_f32 %0, %1, %2" : "=v"(r) : "v"(lo), "v"(hi)); return r; }
; __device__ void phase_norm_alow(const Params& P, int l, int half, LAS unsigned char* lds) {
;     ...
;         for (int i = 0; i < 4; ++i) { f32x4 h = v[i] * r * gv[i];
;             u32x2 w; w.x = cvt_pk_bf16(h[0], h[1]); w.y = cvt_pk_bf16(h[2], h[3]);
;             *(u32x2*)(H + (size_t)row * DM + i * 256 + lane * 4) = w;
; #pragma unroll
;             for (int c = 0; c < 16; ++c) { const f32x4 wv = *(const LAS f32x4*)(WaT + c * 1024 + i * 256 + lane * 4); a[c] += h[0] * wv[0] + h[1] * wv[1] + h[2] * wv[2] + h[3] * wv[3]; } }
	v_pk_fma_f32 v[148:149], v[124:125], v[72:73], v[148:149]
	v_pk_fma_f32 v[148:149], v[126:127], v[68:69], v[148:149]
	s_waitcnt lgkmcnt(6)
	v_pk_fma_f32 v[152:153], v[128:129], v[72:73], v[152:153]
	ds_read_b128 v[116:119], v61 offset:33792
	v_pk_fma_f32 v[152:153], v[130:131], v[68:69], v[152:153]
	ds_read_b128 v[120:123], v61 offset:37888
	s_waitcnt lgkmcnt(7)
	v_pk_fma_f32 v[150:151], v[132:133], v[72:73], v[150:151]
	v_pk_fma_f32 v[150:151], v[134:135], v[68:69], v[150:151]
	s_waitcnt lgkmcnt(6)
	v_pk_fma_f32 v[154:155], v[136:137], v[72:73], v[154:155]
	ds_read_b128 v[124:127], v61 offset:41984
	v_pk_fma_f32 v[154:155], v[138:139], v[68:69], v[154:155]
	ds_read_b128 v[128:131], v61 offset:46080
	s_waitcnt lgkmcnt(7)
	v_pk_fma_f32 v[156:157], v[100:101], v[72:73], v[156:157]
	v_pk_fma_f32 v[156:157], v[102:103], v[68:69], v[156:157]
	s_waitcnt lgkmcnt(6)
	v_pk_fma_f32 v[158:159], v[104:105], v[72:73], v[158:159]
	ds_read_b128 v[132:135], v61 offset:50176
	v_pk_fma_f32 v[158:159], v[106:107], v[68:69], v[158:159]
	ds_read_b128 v[136:139], v61 offset:54272
	s_waitcnt lgkmcnt(7)
	v_pk_fma_f32 v[160:161], v[108:109], v[72:73], v[160:161]
	v_pk_fma_f32 v[160:161], v[110:111], v[68:69], v[160:161]
	s_waitcnt lgkmcnt(6)
	v_pk_fma_f32 v[162:163], v[112:113], v[72:73], v[162:163]
	ds_read_b128 v[100:103], v61 offset:58368
	v_pk_fma_f32 v[162:163], v[114:115], v[68:69], v[162:163]
	ds_read_b128 v[104:107], v61 offset:62464
	s_waitcnt lgkmcnt(7)
	v_pk_fma_f32 v[164:165], v[116:117], v[72:73], v[164:165]
	v_pk_fma_f32 v[164:165], v[118:119], v[68:69], v[164:165]
	s_waitcnt lgkmcnt(6)
	v_pk_fma_f32 v[168:169], v[120:121], v[72:73], v[168:169]
	ds_read_b128 v[108:111], v61 offset:2048
	v_pk_fma_f32 v[168:169], v[122:123], v[68:69], v[168:169]
	ds_read_b128 v[112:115], v61 offset:6144
	s_waitcnt lgkmcnt(7)
	v_pk_fma_f32 v[170:171], v[124:125], v[72:73], v[170:171]
	v_pk_fma_f32 v[170:171], v[126:127], v[68:69], v[170:171]
	s_waitcnt lgkmcnt(6)
	v_pk_fma_f32 v[172:173], v[128:129], v[72:73], v[172:173]
	ds_read_b128 v[116:119], v61 offset:10240
	v_pk_fma_f32 v[172:173], v[130:131], v[68:69], v[172:173]
	ds_read_b128 v[120:123], v61 offset:14336
	s_waitcnt lgkmcnt(7)
	v_pk_fma_f32 v[174:175], v[132:133], v[72:73], v[174:175]
	v_pk_fma_f32 v[174:175], v[134:135], v[68:69], v[174:175]
	s_waitcnt lgkmcnt(6)
	v_pk_fma_f32 v[176:177], v[136:137], v[72:73], v[176:177]
	ds_read_b128 v[124:127], v61 offset:18432
	v_pk_fma_f32 v[176:177], v[138:139], v[68:69], v[176:177]
	ds_read_b128 v[128:131], v61 offset:22528
	s_waitcnt lgkmcnt(7)
	v_pk_fma_f32 v[178:179], v[100:101], v[72:73], v[178:179]
	v_pk_fma_f32 v[178:179], v[102:103], v[68:69], v[178:179]
	s_waitcnt lgkmcnt(6)
	v_pk_fma_f32 v[180:181], v[104:105], v[72:73], v[180:181]
	v_pk_mul_f32 v[38:39], v[38:39], v[60:61] op_sel_hi:[1,0]
	v_pk_mul_f32 v[40:41], v[40:41], v[60:61] op_sel_hi:[1,0]
	v_pk_mul_f32 v[46:47], v[8:9], v[40:41]
	v_pk_mul_f32 v[70:71], v[6:7], v[38:39]
	v_pk_fma_f32 v[180:181], v[106:107], v[68:69], v[180:181]
	v_cvt_pk_bf16_f32 v42, v70, v71
	v_cvt_pk_bf16_f32 v43, v46, v47
	ds_read_b128 v[132:135], v61 offset:26624
	global_store_dwordx2 v[58:59], v[42:43], off offset:1024
	ds_read_b128 v[136:139], v61 offset:30720
	s_waitcnt lgkmcnt(7)
	v_pk_fma_f32 v[148:149], v[108:109], v[70:71], v[148:149]
	v_pk_fma_f32 v[148:149], v[110:111], v[46:47], v[148:149]
	s_waitcnt lgkmcnt(6)
	v_pk_fma_f32 v[152:153], v[112:113], v[70:71], v[152:153]
	ds_read_b128 v[100:103], v61 offset:34816
	v_pk_fma_f32 v[152:153], v[114:115], v[46:47], v[152:153]
	ds_read_b128 v[104:107], v61 offset:38912
	s_waitcnt lgkmcnt(7)
	v_pk_fma_f32 v[150:151], v[116:117], v[70:71], v[150:151]
	v_pk_fma_f32 v[150:151], v[118:119], v[46:47], v[150:151]
	s_waitcnt lgkmcnt(6)
	v_pk_fma_f32 v[154:155], v[120:121], v[70:71], v[154:155]
	ds_read_b128 v[108:111], v61 offset:43008
	v_pk_fma_f32 v[154:155], v[122:123], v[46:47], v[154:155]
	ds_read_b128 v[112:115], v61 offset:47104
	s_waitcnt lgkmcnt(7)
	v_pk_fma_f32 v[156:157], v[124:125], v[70:71], v[156:157]
	v_pk_fma_f32 v[156:157], v[126:127], v[46:47], v[156:157]
	s_waitcnt lgkmcnt(6)
	v_pk_fma_f32 v[158:159], v[128:129], v[70:71], v[158:159]
	ds_read_b128 v[116:119], v61 offset:51200
	v_pk_fma_f32 v[158:159], v[130:131], v[46:47], v[158:159]
	ds_read_b128 v[120:123], v61 offset:55296
	s_waitcnt lgkmcnt(7)
	v_pk_fma_f32 v[160:161], v[132:133], v[70:71], v[160:161]
	v_pk_fma_f32 v[160:161], v[134:135], v[46:47], v[160:161]
	s_waitcnt lgkmcnt(6)
	v_pk_fma_f32 v[162:163], v[136:137], v[70:71], v[162:163]
	ds_read_b128 v[124:127], v61 offset:59392
	v_pk_fma_f32 v[162:163], v[138:139], v[46:47], v[162:163]
	ds_read_b128 v[128:131], v61 offset:63488
	s_waitcnt lgkmcnt(7)
	v_pk_fma_f32 v[164:165], v[100:101], v[70:71], v[164:165]
	v_pk_fma_f32 v[164:165], v[102:103], v[46:47], v[164:165]
	s_waitcnt lgkmcnt(6)
	v_pk_fma_f32 v[168:169], v[104:105], v[70:71], v[168:169]
	ds_read_b128 v[132:135], v61 offset:3072
	v_pk_fma_f32 v[168:169], v[106:107], v[46:47], v[168:169]
	ds_read_b128 v[136:139], v61 offset:7168
	s_waitcnt lgkmcnt(7)
	v_pk_fma_f32 v[170:171], v[108:109], v[70:71], v[170:171]
	v_pk_fma_f32 v[170:171], v[110:111], v[46:47], v[170:171]
	s_waitcnt lgkmcnt(6)
	v_pk_fma_f32 v[172:173], v[112:113], v[70:71], v[172:173]
	ds_read_b128 v[100:103], v61 offset:11264
	v_pk_fma_f32 v[172:173], v[114:115], v[46:47], v[172:173]
	ds_read_b128 v[104:107], v61 offset:15360
	s_waitcnt lgkmcnt(7)
	v_pk_fma_f32 v[174:175], v[116:117], v[70:71], v[174:175]
	v_pk_fma_f32 v[174:175], v[118:119], v[46:47], v[174:175]
	s_waitcnt lgkmcnt(6)
; #define LAS __attribute__((address_space(3)))
; __device__ __forceinline__ unsigned cvt_pk_bf16(float lo, float hi) { unsigned r; asm volatile("v_cvt_pk_bf16_f32 %0, %1, %2" : "=v"(r) : "v"(lo), "v"(hi)); return r; }
; __device__ void phase_norm_alow(const Params& P, int l, int half, LAS unsigned char* lds) {
;     ...
;         for (int i = 0; i < 4; ++i) { f32x4 h = v[i] * r * gv[i];
;             u32x2 w; w.x = cvt_pk_bf16(h[0], h[1]); w.y = cvt_pk_bf16(h[2], h[3]);
;             *(u32x2*)(H + (size_t)row * DM + i * 256 + lane * 4) = w;
; #pragma unroll
;             for (int c = 0; c < 16; ++c) { const f32x4 wv = *(const LAS f32x4*)(WaT + c * 1024 + i * 256 + lane * 4); a[c] += h[0] * wv[0] + h[1] * wv[1] + h[2] * wv[2] + h[3] * wv[3]; } }
;         float b8[8], b4[4], b2[2], b1;
;         { const bool up = (lane & 32) != 0;
; #pragma unroll
;           for (int c = 0; c < 8; ++c) { const float keep = up ? a[c + 8] : a[c], send = up ? a[c] : a[c + 8]; b8[c] = keep + __shfl_xor(send, 32); } }
;         { const bool up = (lane & 16) != 0;
; #pragma unroll
;           for (int c = 0; c < 4; ++c) { const float keep = up ? b8[c + 4] : b8[c], send = up ? b8[c] : b8[c + 4]; b4[c] = keep + __shfl_xor(send, 16); } }
;         { const bool up = (lane & 8) != 0;
; #pragma unroll
;           for (int c = 0; c < 2; ++c) { const float keep = up ? b4[c + 2] : b4[c], send = up ? b4[c] : b4[c + 2]; b2[c] = keep + __shfl_xor(send, 8); } }
;         { const bool up = (lane & 4) != 0; const float keep = up ? b2[1] : b2[0], send = up ? b2[0] : b2[1]; b1 = keep + __shfl_xor(send, 4); }
;         b1 += __shfl_xor(b1, 2); b1 += __shfl_xor(b1, 1);
;         if ((lane & 3) == 0) { const int co = ((lane >> 5) & 1) * 8 + ((lane >> 4) & 1) * 4 + ((lane >> 3) & 1) * 2 + ((lane >> 2) & 1); AL[(size_t)row * 16 + co] = b1; }
	v_pk_fma_f32 v[176:177], v[120:121], v[70:71], v[176:177]
	ds_read_b128 v[108:111], v61 offset:19456
	v_pk_fma_f32 v[176:177], v[122:123], v[46:47], v[176:177]
	ds_read_b128 v[112:115], v61 offset:23552
	s_waitcnt lgkmcnt(7)
	v_pk_fma_f32 v[178:179], v[124:125], v[70:71], v[178:179]
	v_pk_fma_f32 v[178:179], v[126:127], v[46:47], v[178:179]
	v_pk_mul_f32 v[34:35], v[34:35], v[60:61] op_sel_hi:[1,0]
	v_pk_mul_f32 v[36:37], v[36:37], v[60:61] op_sel_hi:[1,0]
	s_waitcnt lgkmcnt(6)
	v_pk_fma_f32 v[180:181], v[128:129], v[70:71], v[180:181]
	v_pk_mul_f32 v[48:49], v[4:5], v[36:37]
	v_pk_mul_f32 v[68:69], v[2:3], v[34:35]
	v_cvt_pk_bf16_f32 v34, v68, v69
	v_cvt_pk_bf16_f32 v35, v48, v49
	ds_read_b128 v[116:119], v61 offset:27648
	v_pk_fma_f32 v[180:181], v[130:131], v[46:47], v[180:181]
	ds_read_b128 v[120:123], v61 offset:31744
	s_waitcnt lgkmcnt(7)
	v_pk_fma_f32 v[148:149], v[132:133], v[68:69], v[148:149]
	v_pk_fma_f32 v[148:149], v[134:135], v[48:49], v[148:149]
	v_add_f32_e32 v45, v148, v149
	s_waitcnt lgkmcnt(6)
	v_pk_fma_f32 v[152:153], v[136:137], v[68:69], v[152:153]
	ds_read_b128 v[124:127], v61 offset:35840
	v_pk_fma_f32 v[152:153], v[138:139], v[48:49], v[152:153]
	v_add_f32_e32 v46, v152, v153
	ds_read_b128 v[128:131], v61 offset:39936
	s_waitcnt lgkmcnt(7)
	v_pk_fma_f32 v[150:151], v[100:101], v[68:69], v[150:151]
	v_pk_fma_f32 v[150:151], v[102:103], v[48:49], v[150:151]
	v_add_f32_e32 v47, v150, v151
	s_waitcnt lgkmcnt(6)
	v_pk_fma_f32 v[154:155], v[104:105], v[68:69], v[154:155]
	ds_read_b128 v[132:135], v61 offset:44032
	v_pk_fma_f32 v[154:155], v[106:107], v[48:49], v[154:155]
	v_add_f32_e32 v51, v154, v155
	ds_read_b128 v[136:139], v61 offset:48128
	s_waitcnt lgkmcnt(7)
	v_pk_fma_f32 v[156:157], v[108:109], v[68:69], v[156:157]
	v_pk_fma_f32 v[156:157], v[110:111], v[48:49], v[156:157]
	v_add_f32_e32 v60, v156, v157
	s_waitcnt lgkmcnt(6)
	v_pk_fma_f32 v[158:159], v[112:113], v[68:69], v[158:159]
	ds_read_b128 v[100:103], v61 offset:52224
	v_pk_fma_f32 v[158:159], v[114:115], v[48:49], v[158:159]
	v_add_f32_e32 v70, v158, v159
	ds_read_b128 v[104:107], v61 offset:56320
	s_waitcnt lgkmcnt(7)
	v_pk_fma_f32 v[160:161], v[116:117], v[68:69], v[160:161]
	v_pk_fma_f32 v[160:161], v[118:119], v[48:49], v[160:161]
	v_add_f32_e32 v71, v160, v161
	s_waitcnt lgkmcnt(6)
	v_pk_fma_f32 v[162:163], v[120:121], v[68:69], v[162:163]
	ds_read_b128 v[108:111], v61 offset:60416
	v_pk_fma_f32 v[162:163], v[122:123], v[48:49], v[162:163]
	v_add_f32_e32 v72, v162, v163
	ds_read_b128 v[112:115], v61 offset:64512
	s_waitcnt lgkmcnt(7)
	v_pk_fma_f32 v[164:165], v[124:125], v[68:69], v[164:165]
	v_pk_fma_f32 v[164:165], v[126:127], v[48:49], v[164:165]
	v_add_f32_e32 v73, v164, v165
	s_waitcnt lgkmcnt(6)
	v_pk_fma_f32 v[168:169], v[128:129], v[68:69], v[168:169]
	v_pk_fma_f32 v[168:169], v[130:131], v[48:49], v[168:169]
	v_add_f32_e32 v74, v168, v169
	s_waitcnt lgkmcnt(5)
	v_pk_fma_f32 v[170:171], v[132:133], v[68:69], v[170:171]
	v_pk_fma_f32 v[170:171], v[134:135], v[48:49], v[170:171]
	v_add_f32_e32 v75, v170, v171
	s_waitcnt lgkmcnt(4)
	v_pk_fma_f32 v[172:173], v[136:137], v[68:69], v[172:173]
	v_pk_fma_f32 v[172:173], v[138:139], v[48:49], v[172:173]
	v_add_f32_e32 v76, v172, v173
	s_waitcnt lgkmcnt(3)
	v_pk_fma_f32 v[174:175], v[100:101], v[68:69], v[174:175]
	v_pk_fma_f32 v[174:175], v[102:103], v[48:49], v[174:175]
	v_add_f32_e32 v77, v174, v175
	s_waitcnt lgkmcnt(2)
	v_pk_fma_f32 v[176:177], v[104:105], v[68:69], v[176:177]
	v_pk_fma_f32 v[176:177], v[106:107], v[48:49], v[176:177]
	v_add_f32_e32 v78, v176, v177
	s_waitcnt lgkmcnt(1)
	v_pk_fma_f32 v[178:179], v[108:109], v[68:69], v[178:179]
	v_pk_fma_f32 v[178:179], v[110:111], v[48:49], v[178:179]
	v_add_f32_e32 v36, v178, v179
	s_waitcnt lgkmcnt(0)
	v_pk_fma_f32 v[180:181], v[112:113], v[68:69], v[180:181]
	v_cndmask_b32_e32 v39, v45, v73, vcc
	ds_bpermute_b32 v39, v62, v39
	v_cndmask_b32_e32 v40, v46, v74, vcc
	ds_bpermute_b32 v40, v62, v40
	v_cndmask_b32_e32 v41, v47, v75, vcc
	v_pk_fma_f32 v[180:181], v[114:115], v[48:49], v[180:181]
	ds_bpermute_b32 v41, v62, v41
	v_cndmask_b32_e32 v42, v51, v76, vcc
	ds_bpermute_b32 v42, v62, v42
	v_cndmask_b32_e32 v43, v60, v77, vcc
	v_add_f32_e32 v37, v180, v181
	v_cndmask_b32_e32 v38, v73, v45, vcc
	ds_bpermute_b32 v43, v62, v43
	v_cndmask_b32_e32 v44, v70, v78, vcc
	s_waitcnt lgkmcnt(4)
	v_add_f32_e32 v38, v38, v39
	v_cndmask_b32_e32 v39, v74, v46, vcc
	ds_bpermute_b32 v44, v62, v44
	s_waitcnt lgkmcnt(4)
	v_add_f32_e32 v39, v39, v40
	v_cndmask_b32_e32 v40, v75, v47, vcc
	s_waitcnt lgkmcnt(3)
	v_add_f32_e32 v40, v40, v41
	v_cndmask_b32_e32 v41, v76, v51, vcc
	s_waitcnt lgkmcnt(2)
	v_add_f32_e32 v41, v41, v42
	v_cndmask_b32_e32 v42, v77, v60, vcc
	s_waitcnt lgkmcnt(1)
	v_add_f32_e32 v42, v42, v43
	v_cndmask_b32_e32 v43, v78, v70, vcc
	s_waitcnt lgkmcnt(0)
	v_add_f32_e32 v43, v43, v44
	v_cndmask_b32_e32 v44, v36, v71, vcc
	v_cndmask_b32_e32 v36, v71, v36, vcc
	v_cndmask_b32_e32 v45, v72, v37, vcc
	ds_bpermute_b32 v36, v62, v36
	ds_bpermute_b32 v45, v62, v45
	v_cndmask_b32_e32 v37, v37, v72, vcc
	v_cndmask_b32_e64 v46, v38, v42, s[36:37]
	v_cndmask_b32_e64 v38, v42, v38, s[36:37]
	s_waitcnt lgkmcnt(1)
	v_add_f32_e32 v36, v44, v36
	s_waitcnt lgkmcnt(0)
	v_add_f32_e32 v37, v37, v45
	v_cndmask_b32_e64 v42, v43, v39, s[36:37]
	v_cndmask_b32_e64 v39, v39, v43, s[36:37]
	v_cndmask_b32_e64 v43, v40, v36, s[36:37]
	v_cndmask_b32_e64 v44, v41, v37, s[36:37]
	ds_bpermute_b32 v46, v63, v46
	ds_bpermute_b32 v39, v63, v39
	ds_bpermute_b32 v43, v63, v43
	ds_bpermute_b32 v44, v63, v44
	v_cndmask_b32_e64 v36, v36, v40, s[36:37]
	v_cndmask_b32_e64 v37, v37, v41, s[36:37]
	s_waitcnt lgkmcnt(3)
	v_add_f32_e32 v38, v38, v46
	s_waitcnt lgkmcnt(2)
	v_add_f32_e32 v39, v42, v39
	s_waitcnt lgkmcnt(1)
	v_add_f32_e32 v36, v36, v43
	s_waitcnt lgkmcnt(0)
	v_add_f32_e32 v37, v37, v44
	v_cndmask_b32_e64 v40, v38, v36, s[38:39]
	v_cndmask_b32_e64 v41, v39, v37, s[38:39]
	ds_bpermute_b32 v40, v64, v40
	ds_bpermute_b32 v41, v64, v41
	v_cndmask_b32_e64 v36, v36, v38, s[38:39]
	v_cndmask_b32_e64 v37, v37, v39, s[38:39]
	global_store_dwordx2 v[58:59], v[34:35], off offset:1536
	s_waitcnt lgkmcnt(1)
	v_add_f32_e32 v36, v36, v40
	s_waitcnt lgkmcnt(0)
	v_add_f32_e32 v37, v37, v41
	v_cndmask_b32_e64 v38, v36, v37, s[40:41]
	ds_bpermute_b32 v38, v65, v38
	v_cndmask_b32_e64 v36, v37, v36, s[40:41]
	s_waitcnt lgkmcnt(0)
	v_add_f32_e32 v36, v36, v38
	s_nop 1
	v_mov_b32_dpp v37, v36 quad_perm:[2,3,0,1] row_mask:0xf bank_mask:0xf
	s_waitcnt lgkmcnt(0)
	v_add_f32_e32 v36, v36, v37
	s_nop 1
	v_mov_b32_dpp v37, v36 quad_perm:[1,0,3,2] row_mask:0xf bank_mask:0xf
	s_and_saveexec_b64 s[0:1], s[42:43]
	s_cbranch_execz .LBB0_752
	v_lshl_add_u64 v[34:35], s[74:75], 0, v[56:57]
	s_waitcnt lgkmcnt(0)
	v_add_f32_e32 v36, v36, v37
	global_store_dword v[34:35], v36, off
	s_branch .LBB0_752
